# non-temporal hint on the f32 residual-stream stores of EpiWo and EpiPle only (x is re-read only after more than a cache's worth of traffic); plus attention packed split
# baseline (speedup 1.0000x reference)
.LBB0_746:
	v_lshl_add_u32 v172, s84, 8, v180
	v_lshl_or_b32 v173, s83, 8, v182
	v_xor_b32_e32 v176, 16, v207
	v_xor_b32_e32 v177, 32, v207
	v_lshlrev_b32_e32 v175, 10, v172
	v_add_u32_e32 v175, v175, v173
	v_lshlrev_b32_e32 v174, 2, v175
	v_lshlrev_b32_e32 v175, 1, v175
	v_lshlrev_b32_e32 v173, 2, v173
	v_lshlrev_b32_e32 v172, 2, v172
	v_lshlrev_b32_e32 v176, 2, v176
	v_lshlrev_b32_e32 v177, 2, v177
	global_load_dwordx4 v[62:65], v173, s[4:5]
	global_load_dwordx4 v[58:61], v173, s[4:5] offset:16
	global_load_dwordx4 v[46:49], v173, s[4:5] offset:512
	global_load_dwordx4 v[34:37], v173, s[4:5] offset:528
	global_load_dwordx4 v[212:215], v174, s[2:3]
	global_load_dwordx4 v[216:219], v174, s[2:3] offset:16
	global_load_dwordx4 v[220:223], v174, s[2:3] offset:512
	global_load_dwordx4 v[224:227], v174, s[2:3] offset:528
	s_add_u32 s86, s2, 0x10000
	s_addc_u32 s87, s3, 0
	global_load_dwordx4 v[228:231], v174, s[86:87]
	global_load_dwordx4 v[232:235], v174, s[86:87] offset:16
	global_load_dwordx4 v[236:239], v174, s[86:87] offset:512
	global_load_dwordx4 v[240:243], v174, s[86:87] offset:528
	s_add_u32 s86, s2, 0x20000
	s_addc_u32 s87, s3, 0
	global_load_dwordx4 v[184:187], v174, s[86:87]
	global_load_dwordx4 v[188:191], v174, s[86:87] offset:16
	global_load_dwordx4 v[192:195], v174, s[86:87] offset:512
	global_load_dwordx4 v[244:247], v174, s[86:87] offset:528
	s_lshl_b32 s13, s83, 2
	s_or_b32 s50, s13, s78
	s_ashr_i32 s51, s50, 31
	s_lshl_b64 s[50:51], s[50:51], 17
	v_readlane_b32 s60, v251, 55
	v_readlane_b32 s61, v251, 56
	s_nop 3
	s_add_u32 s50, s60, s50
	s_addc_u32 s51, s61, s51
	s_waitcnt vmcnt(0)
	v_pk_add_f32 v[142:143], v[142:143], v[212:213]
	v_pk_add_f32 v[144:145], v[144:145], v[214:215]
	v_pk_add_f32 v[138:139], v[138:139], v[216:217]
	v_pk_add_f32 v[140:141], v[140:141], v[218:219]
	v_pk_add_f32 v[134:135], v[134:135], v[220:221]
	v_pk_add_f32 v[136:137], v[136:137], v[222:223]
	v_pk_add_f32 v[130:131], v[130:131], v[224:225]
	v_pk_add_f32 v[132:133], v[132:133], v[226:227]
	global_store_dwordx4 v174, v[142:145], s[16:17] nt
	global_store_dwordx4 v174, v[138:141], s[16:17] offset:16 nt
	global_store_dwordx4 v174, v[134:137], s[16:17] offset:512 nt
	global_store_dwordx4 v174, v[130:133], s[16:17] offset:528 nt
	v_mul_f32_e32 v149, v145, v145
	v_mul_f32_e32 v148, v143, v143
	v_fmac_f32_e32 v148, v142, v142
	v_fmac_f32_e32 v149, v144, v144
	v_add_f32_e32 v148, v148, v149
	v_mul_f32_e32 v149, v139, v139
	v_fmac_f32_e32 v149, v138, v138
	v_add_f32_e32 v148, v148, v149
	v_mul_f32_e32 v149, v141, v141
	v_fmac_f32_e32 v149, v140, v140
	v_add_f32_e32 v178, v149, v148
	v_mul_f32_e32 v149, v137, v137
	v_mul_f32_e32 v148, v135, v135
	v_fmac_f32_e32 v148, v134, v134
	v_fmac_f32_e32 v149, v136, v136
	v_add_f32_e32 v148, v148, v149
	v_mul_f32_e32 v149, v131, v131
	v_fmac_f32_e32 v149, v130, v130
	v_add_f32_e32 v148, v148, v149
	v_mul_f32_e32 v149, v133, v133
	v_fmac_f32_e32 v149, v132, v132
	v_add_f32_e32 v148, v149, v148
	v_add_f32_e32 v178, v178, v148
	ds_bpermute_b32 v179, v176, v178
	v_pk_mul_f32 v[212:213], v[62:63], v[142:143]
	v_pk_mul_f32 v[214:215], v[64:65], v[144:145]
	v_pk_mul_f32 v[216:217], v[58:59], v[138:139]
	v_pk_mul_f32 v[218:219], v[60:61], v[140:141]
	v_pk_mul_f32 v[220:221], v[46:47], v[134:135]
	v_pk_mul_f32 v[222:223], v[48:49], v[136:137]
	v_pk_mul_f32 v[224:225], v[34:35], v[130:131]
	v_pk_mul_f32 v[226:227], v[36:37], v[132:133]
	s_waitcnt lgkmcnt(0)
	v_add_f32_e32 v178, v178, v179
	ds_bpermute_b32 v248, v177, v178
	v_cvt_pk_bf16_f32 v212, v212, v213
	v_cvt_pk_bf16_f32 v213, v214, v215
	v_cvt_pk_bf16_f32 v214, v216, v217
	v_cvt_pk_bf16_f32 v215, v218, v219
	v_cvt_pk_bf16_f32 v220, v220, v221
	v_cvt_pk_bf16_f32 v221, v222, v223
	v_cvt_pk_bf16_f32 v222, v224, v225
	v_cvt_pk_bf16_f32 v223, v226, v227
	global_store_dwordx4 v175, v[212:215], s[34:35]
	global_store_dwordx4 v175, v[220:223], s[34:35] offset:256
	s_waitcnt lgkmcnt(0)
	v_add_f32_e32 v178, v178, v248
	s_and_saveexec_b64 s[58:59], s[40:41]
	global_store_dword v172, v178, s[50:51]
	s_or_b64 exec, exec, s[58:59]
	v_pk_add_f32 v[126:127], v[126:127], v[228:229]
	v_pk_add_f32 v[128:129], v[128:129], v[230:231]
	v_pk_add_f32 v[122:123], v[122:123], v[232:233]
	v_pk_add_f32 v[124:125], v[124:125], v[234:235]
	v_pk_add_f32 v[118:119], v[118:119], v[236:237]
	v_pk_add_f32 v[120:121], v[120:121], v[238:239]
	v_pk_add_f32 v[114:115], v[114:115], v[240:241]
	v_pk_add_f32 v[116:117], v[116:117], v[242:243]
	s_add_u32 s88, s16, 0x10000
	s_addc_u32 s89, s17, 0
	s_add_u32 s90, s34, 0x8000
	s_addc_u32 s91, s35, 0
	global_store_dwordx4 v174, v[126:129], s[88:89] nt
	global_store_dwordx4 v174, v[122:125], s[88:89] offset:16 nt
	global_store_dwordx4 v174, v[118:121], s[88:89] offset:512 nt
	global_store_dwordx4 v174, v[114:117], s[88:89] offset:528 nt
	v_mul_f32_e32 v149, v129, v129
	v_mul_f32_e32 v148, v127, v127
	v_fmac_f32_e32 v148, v126, v126
	v_fmac_f32_e32 v149, v128, v128
	v_add_f32_e32 v148, v148, v149
	v_mul_f32_e32 v149, v123, v123
	v_fmac_f32_e32 v149, v122, v122
	v_add_f32_e32 v148, v148, v149
	v_mul_f32_e32 v149, v125, v125
	v_fmac_f32_e32 v149, v124, v124
	v_add_f32_e32 v178, v149, v148
	v_mul_f32_e32 v149, v121, v121
	v_mul_f32_e32 v148, v119, v119
	v_fmac_f32_e32 v148, v118, v118
	v_fmac_f32_e32 v149, v120, v120
	v_add_f32_e32 v148, v148, v149
	v_mul_f32_e32 v149, v115, v115
	v_fmac_f32_e32 v149, v114, v114
	v_add_f32_e32 v148, v148, v149
	v_mul_f32_e32 v149, v117, v117
	v_fmac_f32_e32 v149, v116, v116
	v_add_f32_e32 v148, v149, v148
	v_add_f32_e32 v178, v178, v148
	ds_bpermute_b32 v179, v176, v178
	v_pk_mul_f32 v[228:229], v[62:63], v[126:127]
	v_pk_mul_f32 v[230:231], v[64:65], v[128:129]
	v_pk_mul_f32 v[232:233], v[58:59], v[122:123]
	v_pk_mul_f32 v[234:235], v[60:61], v[124:125]
	v_pk_mul_f32 v[236:237], v[46:47], v[118:119]
	v_pk_mul_f32 v[238:239], v[48:49], v[120:121]
	v_pk_mul_f32 v[240:241], v[34:35], v[114:115]
	v_pk_mul_f32 v[242:243], v[36:37], v[116:117]
	s_waitcnt lgkmcnt(0)
	v_add_f32_e32 v178, v178, v179
	ds_bpermute_b32 v248, v177, v178
	v_cvt_pk_bf16_f32 v228, v228, v229
	v_cvt_pk_bf16_f32 v229, v230, v231
	v_cvt_pk_bf16_f32 v230, v232, v233
	v_cvt_pk_bf16_f32 v231, v234, v235
	v_cvt_pk_bf16_f32 v236, v236, v237
	v_cvt_pk_bf16_f32 v237, v238, v239
	v_cvt_pk_bf16_f32 v238, v240, v241
	v_cvt_pk_bf16_f32 v239, v242, v243
	global_store_dwordx4 v175, v[228:231], s[90:91]
	global_store_dwordx4 v175, v[236:239], s[90:91] offset:256
	s_waitcnt lgkmcnt(0)
	v_add_f32_e32 v178, v178, v248
	s_and_saveexec_b64 s[58:59], s[40:41]
	global_store_dword v172, v178, s[50:51] offset:64
	s_or_b64 exec, exec, s[58:59]
	v_pk_add_f32 v[110:111], v[110:111], v[184:185]
	v_pk_add_f32 v[112:113], v[112:113], v[186:187]
	v_pk_add_f32 v[106:107], v[106:107], v[188:189]
	v_pk_add_f32 v[108:109], v[108:109], v[190:191]
	v_pk_add_f32 v[102:103], v[102:103], v[192:193]
	v_pk_add_f32 v[104:105], v[104:105], v[194:195]
	v_pk_add_f32 v[98:99], v[98:99], v[244:245]
	v_pk_add_f32 v[100:101], v[100:101], v[246:247]
	s_add_u32 s88, s16, 0x20000
	s_addc_u32 s89, s17, 0
	s_add_u32 s90, s34, 0x10000
	s_addc_u32 s91, s35, 0
	global_store_dwordx4 v174, v[110:113], s[88:89] nt
	global_store_dwordx4 v174, v[106:109], s[88:89] offset:16 nt
	global_store_dwordx4 v174, v[102:105], s[88:89] offset:512 nt
	global_store_dwordx4 v174, v[98:101], s[88:89] offset:528 nt
	v_mul_f32_e32 v149, v113, v113
	v_mul_f32_e32 v148, v111, v111
	v_fmac_f32_e32 v148, v110, v110
	v_fmac_f32_e32 v149, v112, v112
	v_add_f32_e32 v148, v148, v149
	v_mul_f32_e32 v149, v107, v107
	v_fmac_f32_e32 v149, v106, v106
	v_add_f32_e32 v148, v148, v149
	v_mul_f32_e32 v149, v109, v109
	v_fmac_f32_e32 v149, v108, v108
	v_add_f32_e32 v178, v149, v148
	v_mul_f32_e32 v149, v105, v105
	v_mul_f32_e32 v148, v103, v103
	v_fmac_f32_e32 v148, v102, v102
	v_fmac_f32_e32 v149, v104, v104
	v_add_f32_e32 v148, v148, v149
	v_mul_f32_e32 v149, v99, v99
	v_fmac_f32_e32 v149, v98, v98
	v_add_f32_e32 v148, v148, v149
	v_mul_f32_e32 v149, v101, v101
	v_fmac_f32_e32 v149, v100, v100
	v_add_f32_e32 v148, v149, v148
	v_add_f32_e32 v178, v178, v148
	ds_bpermute_b32 v179, v176, v178
	v_pk_mul_f32 v[184:185], v[62:63], v[110:111]
	v_pk_mul_f32 v[186:187], v[64:65], v[112:113]
	v_pk_mul_f32 v[188:189], v[58:59], v[106:107]
	v_pk_mul_f32 v[190:191], v[60:61], v[108:109]
	v_pk_mul_f32 v[192:193], v[46:47], v[102:103]
	v_pk_mul_f32 v[194:195], v[48:49], v[104:105]
	v_pk_mul_f32 v[244:245], v[34:35], v[98:99]
	v_pk_mul_f32 v[246:247], v[36:37], v[100:101]
	s_waitcnt lgkmcnt(0)
	v_add_f32_e32 v178, v178, v179
	ds_bpermute_b32 v248, v177, v178
	v_cvt_pk_bf16_f32 v184, v184, v185
	v_cvt_pk_bf16_f32 v185, v186, v187
	v_cvt_pk_bf16_f32 v186, v188, v189
	v_cvt_pk_bf16_f32 v187, v190, v191
	v_cvt_pk_bf16_f32 v192, v192, v193
	v_cvt_pk_bf16_f32 v193, v194, v195
	v_cvt_pk_bf16_f32 v194, v244, v245
	v_cvt_pk_bf16_f32 v195, v246, v247
	global_store_dwordx4 v175, v[184:187], s[90:91]
	global_store_dwordx4 v175, v[192:195], s[90:91] offset:256
	s_waitcnt lgkmcnt(0)
	v_add_f32_e32 v178, v178, v248
	s_and_saveexec_b64 s[58:59], s[40:41]
	global_store_dword v172, v178, s[50:51] offset:128
	s_or_b64 exec, exec, s[58:59]
	s_add_u32 s86, s2, 0x30000
	s_addc_u32 s87, s3, 0
	global_load_dwordx4 v[212:215], v174, s[86:87]
	global_load_dwordx4 v[216:219], v174, s[86:87] offset:16
	global_load_dwordx4 v[220:223], v174, s[86:87] offset:512
	global_load_dwordx4 v[224:227], v174, s[86:87] offset:528
	s_add_u32 s86, s2, 0x80000
	s_addc_u32 s87, s3, 0
	global_load_dwordx4 v[228:231], v174, s[86:87]
	global_load_dwordx4 v[232:235], v174, s[86:87] offset:16
	global_load_dwordx4 v[236:239], v174, s[86:87] offset:512
	global_load_dwordx4 v[240:243], v174, s[86:87] offset:528
	s_add_u32 s86, s2, 0x90000
	s_addc_u32 s87, s3, 0
	global_load_dwordx4 v[184:187], v174, s[86:87]
	global_load_dwordx4 v[188:191], v174, s[86:87] offset:16
	global_load_dwordx4 v[192:195], v174, s[86:87] offset:512
	global_load_dwordx4 v[244:247], v174, s[86:87] offset:528
	s_waitcnt vmcnt(0)
	v_pk_add_f32 v[94:95], v[94:95], v[212:213]
	v_pk_add_f32 v[96:97], v[96:97], v[214:215]
	v_pk_add_f32 v[90:91], v[90:91], v[216:217]
	v_pk_add_f32 v[92:93], v[92:93], v[218:219]
	v_pk_add_f32 v[86:87], v[86:87], v[220:221]
	v_pk_add_f32 v[88:89], v[88:89], v[222:223]
	v_pk_add_f32 v[82:83], v[82:83], v[224:225]
	v_pk_add_f32 v[84:85], v[84:85], v[226:227]
	s_add_u32 s88, s16, 0x30000
	s_addc_u32 s89, s17, 0
	s_add_u32 s90, s34, 0x18000
	s_addc_u32 s91, s35, 0
	global_store_dwordx4 v174, v[94:97], s[88:89] nt
	global_store_dwordx4 v174, v[90:93], s[88:89] offset:16 nt
	global_store_dwordx4 v174, v[86:89], s[88:89] offset:512 nt
	global_store_dwordx4 v174, v[82:85], s[88:89] offset:528 nt
	v_mul_f32_e32 v149, v97, v97
	v_mul_f32_e32 v148, v95, v95
	v_fmac_f32_e32 v148, v94, v94
	v_fmac_f32_e32 v149, v96, v96
	v_add_f32_e32 v148, v148, v149
	v_mul_f32_e32 v149, v91, v91
	v_fmac_f32_e32 v149, v90, v90
	v_add_f32_e32 v148, v148, v149
	v_mul_f32_e32 v149, v93, v93
	v_fmac_f32_e32 v149, v92, v92
	v_add_f32_e32 v178, v149, v148
	v_mul_f32_e32 v149, v89, v89
	v_mul_f32_e32 v148, v87, v87
	v_fmac_f32_e32 v148, v86, v86
	v_fmac_f32_e32 v149, v88, v88
	v_add_f32_e32 v148, v148, v149
	v_mul_f32_e32 v149, v83, v83
	v_fmac_f32_e32 v149, v82, v82
	v_add_f32_e32 v148, v148, v149
	v_mul_f32_e32 v149, v85, v85
	v_fmac_f32_e32 v149, v84, v84
	v_add_f32_e32 v148, v149, v148
	v_add_f32_e32 v178, v178, v148
	ds_bpermute_b32 v179, v176, v178
	v_pk_mul_f32 v[212:213], v[62:63], v[94:95]
	v_pk_mul_f32 v[214:215], v[64:65], v[96:97]
	v_pk_mul_f32 v[216:217], v[58:59], v[90:91]
	v_pk_mul_f32 v[218:219], v[60:61], v[92:93]
	v_pk_mul_f32 v[220:221], v[46:47], v[86:87]
	v_pk_mul_f32 v[222:223], v[48:49], v[88:89]
	v_pk_mul_f32 v[224:225], v[34:35], v[82:83]
	v_pk_mul_f32 v[226:227], v[36:37], v[84:85]
	s_waitcnt lgkmcnt(0)
	v_add_f32_e32 v178, v178, v179
	ds_bpermute_b32 v248, v177, v178
	v_cvt_pk_bf16_f32 v212, v212, v213
	v_cvt_pk_bf16_f32 v213, v214, v215
	v_cvt_pk_bf16_f32 v214, v216, v217
	v_cvt_pk_bf16_f32 v215, v218, v219
	v_cvt_pk_bf16_f32 v220, v220, v221
	v_cvt_pk_bf16_f32 v221, v222, v223
	v_cvt_pk_bf16_f32 v222, v224, v225
	v_cvt_pk_bf16_f32 v223, v226, v227
	global_store_dwordx4 v175, v[212:215], s[90:91]
	global_store_dwordx4 v175, v[220:223], s[90:91] offset:256
	s_waitcnt lgkmcnt(0)
	v_add_f32_e32 v178, v178, v248
	s_and_saveexec_b64 s[58:59], s[40:41]
	global_store_dword v172, v178, s[50:51] offset:192
	s_or_b64 exec, exec, s[58:59]
	v_pk_add_f32 v[78:79], v[78:79], v[228:229]
	v_pk_add_f32 v[80:81], v[80:81], v[230:231]
	v_pk_add_f32 v[74:75], v[74:75], v[232:233]
	v_pk_add_f32 v[76:77], v[76:77], v[234:235]
	v_pk_add_f32 v[70:71], v[70:71], v[236:237]
	v_pk_add_f32 v[72:73], v[72:73], v[238:239]
	v_pk_add_f32 v[66:67], v[66:67], v[240:241]
	v_pk_add_f32 v[68:69], v[68:69], v[242:243]
	s_add_u32 s88, s16, 0x80000
	s_addc_u32 s89, s17, 0
	s_add_u32 s90, s34, 0x40000
	s_addc_u32 s91, s35, 0
	global_store_dwordx4 v174, v[78:81], s[88:89] nt
	global_store_dwordx4 v174, v[74:77], s[88:89] offset:16 nt
	global_store_dwordx4 v174, v[70:73], s[88:89] offset:512 nt
	global_store_dwordx4 v174, v[66:69], s[88:89] offset:528 nt
	v_mul_f32_e32 v149, v81, v81
	v_mul_f32_e32 v148, v79, v79
	v_fmac_f32_e32 v148, v78, v78
	v_fmac_f32_e32 v149, v80, v80
	v_add_f32_e32 v148, v148, v149
	v_mul_f32_e32 v149, v75, v75
	v_fmac_f32_e32 v149, v74, v74
	v_add_f32_e32 v148, v148, v149
	v_mul_f32_e32 v149, v77, v77
	v_fmac_f32_e32 v149, v76, v76
	v_add_f32_e32 v178, v149, v148
	v_mul_f32_e32 v149, v73, v73
	v_mul_f32_e32 v148, v71, v71
	v_fmac_f32_e32 v148, v70, v70
	v_fmac_f32_e32 v149, v72, v72
	v_add_f32_e32 v148, v148, v149
	v_mul_f32_e32 v149, v67, v67
	v_fmac_f32_e32 v149, v66, v66
	v_add_f32_e32 v148, v148, v149
	v_mul_f32_e32 v149, v69, v69
	v_fmac_f32_e32 v149, v68, v68
	v_add_f32_e32 v148, v149, v148
	v_add_f32_e32 v178, v178, v148
	ds_bpermute_b32 v179, v176, v178
	v_pk_mul_f32 v[228:229], v[62:63], v[78:79]
	v_pk_mul_f32 v[230:231], v[64:65], v[80:81]
	v_pk_mul_f32 v[232:233], v[58:59], v[74:75]
	v_pk_mul_f32 v[234:235], v[60:61], v[76:77]
	v_pk_mul_f32 v[236:237], v[46:47], v[70:71]
	v_pk_mul_f32 v[238:239], v[48:49], v[72:73]
	v_pk_mul_f32 v[240:241], v[34:35], v[66:67]
	v_pk_mul_f32 v[242:243], v[36:37], v[68:69]
	s_waitcnt lgkmcnt(0)
	v_add_f32_e32 v178, v178, v179
	ds_bpermute_b32 v248, v177, v178
	v_cvt_pk_bf16_f32 v228, v228, v229
	v_cvt_pk_bf16_f32 v229, v230, v231
	v_cvt_pk_bf16_f32 v230, v232, v233
	v_cvt_pk_bf16_f32 v231, v234, v235
	v_cvt_pk_bf16_f32 v236, v236, v237
	v_cvt_pk_bf16_f32 v237, v238, v239
	v_cvt_pk_bf16_f32 v238, v240, v241
	v_cvt_pk_bf16_f32 v239, v242, v243
	global_store_dwordx4 v175, v[228:231], s[90:91]
	global_store_dwordx4 v175, v[236:239], s[90:91] offset:256
	s_waitcnt lgkmcnt(0)
	v_add_f32_e32 v178, v178, v248
	s_and_saveexec_b64 s[58:59], s[40:41]
	global_store_dword v172, v178, s[50:51] offset:512
	s_or_b64 exec, exec, s[58:59]
	v_pk_add_f32 v[54:55], v[54:55], v[184:185]
	v_pk_add_f32 v[56:57], v[56:57], v[186:187]
	v_pk_add_f32 v[50:51], v[50:51], v[188:189]
	v_pk_add_f32 v[52:53], v[52:53], v[190:191]
	v_pk_add_f32 v[42:43], v[42:43], v[192:193]
	v_pk_add_f32 v[44:45], v[44:45], v[194:195]
	v_pk_add_f32 v[38:39], v[38:39], v[244:245]
	v_pk_add_f32 v[40:41], v[40:41], v[246:247]
	s_add_u32 s88, s16, 0x90000
	s_addc_u32 s89, s17, 0
	s_add_u32 s90, s34, 0x48000
	s_addc_u32 s91, s35, 0
	global_store_dwordx4 v174, v[54:57], s[88:89] nt
	global_store_dwordx4 v174, v[50:53], s[88:89] offset:16 nt
	global_store_dwordx4 v174, v[42:45], s[88:89] offset:512 nt
	global_store_dwordx4 v174, v[38:41], s[88:89] offset:528 nt
	v_mul_f32_e32 v149, v57, v57
	v_mul_f32_e32 v148, v55, v55
	v_fmac_f32_e32 v148, v54, v54
	v_fmac_f32_e32 v149, v56, v56
	v_add_f32_e32 v148, v148, v149
	v_mul_f32_e32 v149, v51, v51
	v_fmac_f32_e32 v149, v50, v50
	v_add_f32_e32 v148, v148, v149
	v_mul_f32_e32 v149, v53, v53
	v_fmac_f32_e32 v149, v52, v52
	v_add_f32_e32 v178, v149, v148
	v_mul_f32_e32 v149, v45, v45
	v_mul_f32_e32 v148, v43, v43
	v_fmac_f32_e32 v148, v42, v42
	v_fmac_f32_e32 v149, v44, v44
	v_add_f32_e32 v148, v148, v149
	v_mul_f32_e32 v149, v39, v39
	v_fmac_f32_e32 v149, v38, v38
	v_add_f32_e32 v148, v148, v149
	v_mul_f32_e32 v149, v41, v41
	v_fmac_f32_e32 v149, v40, v40
	v_add_f32_e32 v148, v149, v148
	v_add_f32_e32 v178, v178, v148
	ds_bpermute_b32 v179, v176, v178
	v_pk_mul_f32 v[184:185], v[62:63], v[54:55]
	v_pk_mul_f32 v[186:187], v[64:65], v[56:57]
	v_pk_mul_f32 v[188:189], v[58:59], v[50:51]
	v_pk_mul_f32 v[190:191], v[60:61], v[52:53]
	v_pk_mul_f32 v[192:193], v[46:47], v[42:43]
	v_pk_mul_f32 v[194:195], v[48:49], v[44:45]
	v_pk_mul_f32 v[244:245], v[34:35], v[38:39]
	v_pk_mul_f32 v[246:247], v[36:37], v[40:41]
	s_waitcnt lgkmcnt(0)
	v_add_f32_e32 v178, v178, v179
	ds_bpermute_b32 v248, v177, v178
	v_cvt_pk_bf16_f32 v184, v184, v185
	v_cvt_pk_bf16_f32 v185, v186, v187
	v_cvt_pk_bf16_f32 v186, v188, v189
	v_cvt_pk_bf16_f32 v187, v190, v191
	v_cvt_pk_bf16_f32 v192, v192, v193
	v_cvt_pk_bf16_f32 v193, v194, v195
	v_cvt_pk_bf16_f32 v194, v244, v245
	v_cvt_pk_bf16_f32 v195, v246, v247
	global_store_dwordx4 v175, v[184:187], s[90:91]
	global_store_dwordx4 v175, v[192:195], s[90:91] offset:256
	s_waitcnt lgkmcnt(0)
	v_add_f32_e32 v178, v178, v248
	s_and_saveexec_b64 s[58:59], s[40:41]
	global_store_dword v172, v178, s[50:51] offset:576
	s_or_b64 exec, exec, s[58:59]
	s_add_u32 s86, s2, 0xa0000
	s_addc_u32 s87, s3, 0
	global_load_dwordx4 v[212:215], v174, s[86:87]
	global_load_dwordx4 v[216:219], v174, s[86:87] offset:16
	global_load_dwordx4 v[220:223], v174, s[86:87] offset:512
	global_load_dwordx4 v[224:227], v174, s[86:87] offset:528
	s_add_u32 s86, s2, 0xb0000
	s_addc_u32 s87, s3, 0
	global_load_dwordx4 v[228:231], v174, s[86:87]
	global_load_dwordx4 v[232:235], v174, s[86:87] offset:16
	global_load_dwordx4 v[236:239], v174, s[86:87] offset:512
	global_load_dwordx4 v[240:243], v174, s[86:87] offset:528
	s_waitcnt vmcnt(0)
	v_pk_add_f32 v[30:31], v[30:31], v[212:213]
	v_pk_add_f32 v[32:33], v[32:33], v[214:215]
	v_pk_add_f32 v[26:27], v[26:27], v[216:217]
	v_pk_add_f32 v[28:29], v[28:29], v[218:219]
	v_pk_add_f32 v[22:23], v[22:23], v[220:221]
	v_pk_add_f32 v[24:25], v[24:25], v[222:223]
	v_pk_add_f32 v[18:19], v[18:19], v[224:225]
	v_pk_add_f32 v[20:21], v[20:21], v[226:227]
	s_add_u32 s88, s16, 0xa0000
	s_addc_u32 s89, s17, 0
	s_add_u32 s90, s34, 0x50000
	s_addc_u32 s91, s35, 0
	global_store_dwordx4 v174, v[30:33], s[88:89] nt
	global_store_dwordx4 v174, v[26:29], s[88:89] offset:16 nt
	global_store_dwordx4 v174, v[22:25], s[88:89] offset:512 nt
	global_store_dwordx4 v174, v[18:21], s[88:89] offset:528 nt
	v_mul_f32_e32 v149, v33, v33
	v_mul_f32_e32 v148, v31, v31
	v_fmac_f32_e32 v148, v30, v30
	v_fmac_f32_e32 v149, v32, v32
	v_add_f32_e32 v148, v148, v149
	v_mul_f32_e32 v149, v27, v27
	v_fmac_f32_e32 v149, v26, v26
	v_add_f32_e32 v148, v148, v149
	v_mul_f32_e32 v149, v29, v29
	v_fmac_f32_e32 v149, v28, v28
	v_add_f32_e32 v178, v149, v148
	v_mul_f32_e32 v149, v25, v25
	v_mul_f32_e32 v148, v23, v23
	v_fmac_f32_e32 v148, v22, v22
	v_fmac_f32_e32 v149, v24, v24
	v_add_f32_e32 v148, v148, v149
	v_mul_f32_e32 v149, v19, v19
	v_fmac_f32_e32 v149, v18, v18
	v_add_f32_e32 v148, v148, v149
	v_mul_f32_e32 v149, v21, v21
	v_fmac_f32_e32 v149, v20, v20
	v_add_f32_e32 v148, v149, v148
	v_add_f32_e32 v178, v178, v148
	ds_bpermute_b32 v179, v176, v178
	v_pk_mul_f32 v[212:213], v[62:63], v[30:31]
	v_pk_mul_f32 v[214:215], v[64:65], v[32:33]
	v_pk_mul_f32 v[216:217], v[58:59], v[26:27]
	v_pk_mul_f32 v[218:219], v[60:61], v[28:29]
	v_pk_mul_f32 v[220:221], v[46:47], v[22:23]
	v_pk_mul_f32 v[222:223], v[48:49], v[24:25]
	v_pk_mul_f32 v[224:225], v[34:35], v[18:19]
	v_pk_mul_f32 v[226:227], v[36:37], v[20:21]
	s_waitcnt lgkmcnt(0)
	v_add_f32_e32 v178, v178, v179
	ds_bpermute_b32 v248, v177, v178
	v_cvt_pk_bf16_f32 v212, v212, v213
	v_cvt_pk_bf16_f32 v213, v214, v215
	v_cvt_pk_bf16_f32 v214, v216, v217
	v_cvt_pk_bf16_f32 v215, v218, v219
	v_cvt_pk_bf16_f32 v220, v220, v221
	v_cvt_pk_bf16_f32 v221, v222, v223
	v_cvt_pk_bf16_f32 v222, v224, v225
	v_cvt_pk_bf16_f32 v223, v226, v227
	global_store_dwordx4 v175, v[212:215], s[90:91]
	global_store_dwordx4 v175, v[220:223], s[90:91] offset:256
	s_waitcnt lgkmcnt(0)
	v_add_f32_e32 v178, v178, v248
	s_and_saveexec_b64 s[58:59], s[40:41]
	global_store_dword v172, v178, s[50:51] offset:640
	s_or_b64 exec, exec, s[58:59]
	v_pk_add_f32 v[14:15], v[14:15], v[228:229]
	v_pk_add_f32 v[16:17], v[16:17], v[230:231]
	v_pk_add_f32 v[10:11], v[10:11], v[232:233]
	v_pk_add_f32 v[12:13], v[12:13], v[234:235]
	v_pk_add_f32 v[6:7], v[6:7], v[236:237]
	v_pk_add_f32 v[8:9], v[8:9], v[238:239]
	v_pk_add_f32 v[2:3], v[2:3], v[240:241]
	v_pk_add_f32 v[4:5], v[4:5], v[242:243]
	s_add_u32 s88, s16, 0xb0000
	s_addc_u32 s89, s17, 0
	s_add_u32 s90, s34, 0x58000
	s_addc_u32 s91, s35, 0
	global_store_dwordx4 v174, v[14:17], s[88:89] nt
	global_store_dwordx4 v174, v[10:13], s[88:89] offset:16 nt
	global_store_dwordx4 v174, v[6:9], s[88:89] offset:512 nt
	global_store_dwordx4 v174, v[2:5], s[88:89] offset:528 nt
	v_mul_f32_e32 v149, v17, v17
	v_mul_f32_e32 v148, v15, v15
	v_fmac_f32_e32 v148, v14, v14
	v_fmac_f32_e32 v149, v16, v16
	v_add_f32_e32 v148, v148, v149
	v_mul_f32_e32 v149, v11, v11
	v_fmac_f32_e32 v149, v10, v10
	v_add_f32_e32 v148, v148, v149
	v_mul_f32_e32 v149, v13, v13
	v_fmac_f32_e32 v149, v12, v12
	v_add_f32_e32 v178, v149, v148
	v_mul_f32_e32 v149, v9, v9
	v_mul_f32_e32 v148, v7, v7
	v_fmac_f32_e32 v148, v6, v6
	v_fmac_f32_e32 v149, v8, v8
	v_add_f32_e32 v148, v148, v149
	v_mul_f32_e32 v149, v3, v3
	v_fmac_f32_e32 v149, v2, v2
	v_add_f32_e32 v148, v148, v149
	v_mul_f32_e32 v149, v5, v5
	v_fmac_f32_e32 v149, v4, v4
	v_add_f32_e32 v148, v149, v148
	v_add_f32_e32 v178, v178, v148
	ds_bpermute_b32 v179, v176, v178
	v_pk_mul_f32 v[228:229], v[62:63], v[14:15]
	v_pk_mul_f32 v[230:231], v[64:65], v[16:17]
	v_pk_mul_f32 v[232:233], v[58:59], v[10:11]
	v_pk_mul_f32 v[234:235], v[60:61], v[12:13]
	v_pk_mul_f32 v[236:237], v[46:47], v[6:7]
	v_pk_mul_f32 v[238:239], v[48:49], v[8:9]
	v_pk_mul_f32 v[240:241], v[34:35], v[2:3]
	v_pk_mul_f32 v[242:243], v[36:37], v[4:5]
	s_waitcnt lgkmcnt(0)
	v_add_f32_e32 v178, v178, v179
	ds_bpermute_b32 v248, v177, v178
	v_cvt_pk_bf16_f32 v228, v228, v229
	v_cvt_pk_bf16_f32 v229, v230, v231
	v_cvt_pk_bf16_f32 v230, v232, v233
	v_cvt_pk_bf16_f32 v231, v234, v235
	v_cvt_pk_bf16_f32 v236, v236, v237
	v_cvt_pk_bf16_f32 v237, v238, v239
	v_cvt_pk_bf16_f32 v238, v240, v241
	v_cvt_pk_bf16_f32 v239, v242, v243
	global_store_dwordx4 v175, v[228:231], s[90:91]
	global_store_dwordx4 v175, v[236:239], s[90:91] offset:256
	s_waitcnt lgkmcnt(0)
	v_add_f32_e32 v178, v178, v248
	s_and_saveexec_b64 s[58:59], s[40:41]
	global_store_dword v172, v178, s[50:51] offset:704
	s_or_b64 exec, exec, s[58:59]
	s_andn2_b64 vcc, exec, s[42:43]
	s_mov_b64 s[42:43], -1
	s_cbranch_vccnz .LBB0_734
	s_andn2_b64 vcc, exec, s[0:1]
	s_cbranch_vccnz .LBB0_733
	s_barrier
	s_branch .LBB0_733

.LBB0_975:
	v_lshl_add_u32 v172, s77, 8, v212
	v_ashrrev_i32_e32 v173, 31, v172
	v_lshlrev_b64 v[148:149], 10, v[172:173]
	v_lshl_add_u64 v[176:177], v[148:149], 0, v[182:183]
	v_lshl_add_u64 v[148:149], v[176:177], 1, s[36:37]
	v_lshl_add_u64 v[186:187], v[176:177], 2, s[16:17]
	global_load_dwordx4 v[188:191], v[148:149], off
	global_load_dwordx4 v[192:195], v[186:187], off
	global_load_dwordx4 v[218:221], v[186:187], off offset:16
	s_waitcnt lgkmcnt(0)
	v_mul_f32_e32 v142, v142, v184
	v_mul_f32_e32 v138, v138, v184
	v_mul_f32_e32 v143, v143, v184
	v_mul_f32_e32 v139, v139, v184
	v_mul_f32_e32 v144, v144, v184
	v_mul_f32_e32 v140, v140, v184
	v_mul_f32_e32 v145, v145, v184
	v_mul_f32_e32 v141, v141, v184
	v_mul_f32_e32 v142, 0xbfb8aa3b, v142
	v_mul_f32_e32 v138, 0xbfb8aa3b, v138
	v_mul_f32_e32 v143, 0xbfb8aa3b, v143
	v_mul_f32_e32 v139, 0xbfb8aa3b, v139
	v_mul_f32_e32 v144, 0xbfb8aa3b, v144
	v_mul_f32_e32 v140, 0xbfb8aa3b, v140
	v_mul_f32_e32 v145, 0xbfb8aa3b, v145
	v_mul_f32_e32 v141, 0xbfb8aa3b, v141
	v_exp_f32_e32 v142, v142
	v_exp_f32_e32 v138, v138
	v_exp_f32_e32 v143, v143
	v_exp_f32_e32 v139, v139
	v_exp_f32_e32 v144, v144
	v_exp_f32_e32 v140, v140
	v_exp_f32_e32 v145, v145
	v_exp_f32_e32 v141, v141
	v_add_f32_e32 v142, 1.0, v142
	v_add_f32_e32 v148, 1.0, v138
	v_add_f32_e32 v143, 1.0, v143
	v_add_f32_e32 v139, 1.0, v139
	v_add_f32_e32 v149, 1.0, v144
	v_add_f32_e32 v217, 1.0, v140
	v_add_f32_e32 v145, 1.0, v145
	v_add_f32_e32 v222, 1.0, v141
	v_rcp_f32_e32 v138, v142
	v_rcp_f32_e32 v140, v148
	v_rcp_f32_e32 v142, v143
	v_rcp_f32_e32 v144, v139
	v_rcp_f32_e32 v139, v149
	v_rcp_f32_e32 v141, v217
	v_rcp_f32_e32 v143, v145
	v_rcp_f32_e32 v145, v222
	s_and_b64 vcc, exec, s[2:3]
	v_mov_b32_e32 v217, 0
	s_waitcnt vmcnt(0)
	v_lshlrev_b32_e32 v149, 16, v189
	v_lshlrev_b32_e32 v148, 16, v188
	v_and_b32_e32 v223, 0xffff0000, v189
	v_and_b32_e32 v222, 0xffff0000, v188
	v_mov_b32_e32 v188, v192
	v_mov_b32_e32 v189, v194
	v_mov_b32_e32 v194, v193
	v_lshlrev_b32_e32 v225, 16, v191
	v_lshlrev_b32_e32 v224, 16, v190
	v_and_b32_e32 v227, 0xffff0000, v191
	v_and_b32_e32 v226, 0xffff0000, v190
	v_mov_b32_e32 v190, v218
	v_mov_b32_e32 v191, v220
	v_mov_b32_e32 v220, v219
	v_pk_fma_f32 v[188:189], v[138:139], v[148:149], v[188:189]
	v_pk_fma_f32 v[192:193], v[142:143], v[222:223], v[194:195]
	v_pk_fma_f32 v[190:191], v[140:141], v[224:225], v[190:191]
	v_pk_fma_f32 v[194:195], v[144:145], v[226:227], v[220:221]
	v_mov_b32_e32 v142, v188
	v_mov_b32_e32 v143, v192
	v_mov_b32_e32 v144, v189
	v_mov_b32_e32 v145, v193
	v_mov_b32_e32 v138, v190
	v_mov_b32_e32 v139, v194
	v_mov_b32_e32 v140, v191
	v_mov_b32_e32 v141, v195
	global_store_dwordx4 v[186:187], v[142:145], off nt
	global_store_dwordx4 v[186:187], v[138:141], off offset:16 nt
	s_cbranch_vccnz .LBB0_977
	v_pk_mul_f32 v[148:149], v[192:193], v[192:193]
	v_pk_mul_f32 v[144:145], v[64:65], v[144:145]
	v_pk_fma_f32 v[148:149], v[188:189], v[188:189], v[148:149]
	v_pk_mul_f32 v[188:189], v[194:195], v[194:195]
	v_add_f32_e32 v148, v148, v149
	v_pk_fma_f32 v[188:189], v[190:191], v[190:191], v[188:189]
	v_pk_mul_f32 v[142:143], v[62:63], v[142:143]
	v_add_f32_e32 v148, v188, v148
	v_add_f32_e32 v217, v189, v148
	v_pk_mul_f32 v[148:149], v[60:61], v[140:141]
	v_pk_mul_f32 v[140:141], v[58:59], v[138:139]
	v_cvt_pk_bf16_f32 v138, v142, v143
	v_cvt_pk_bf16_f32 v139, v144, v145
	v_cvt_pk_bf16_f32 v140, v140, v141
	v_cvt_pk_bf16_f32 v141, v148, v149
	v_lshl_add_u64 v[142:143], v[176:177], 1, s[30:31]
	global_store_dwordx4 v[142:143], v[138:141], off
.LBB0_977:
	s_nop 1
	v_or_b32_e32 v138, 0x80, v176
	v_mov_b32_e32 v139, v177
	v_lshl_add_u64 v[140:141], v[138:139], 1, s[36:37]
	global_load_dwordx4 v[140:143], v[140:141], off
	s_nop 0
	global_load_dwordx4 v[188:191], v[186:187], off offset:512
	global_load_dwordx4 v[192:195], v[186:187], off offset:528
	v_mul_f32_e32 v134, v134, v184
	v_mul_f32_e32 v130, v130, v184
	v_mul_f32_e32 v135, v135, v184
	v_mul_f32_e32 v131, v131, v184
	v_mul_f32_e32 v136, v136, v184
	v_mul_f32_e32 v132, v132, v184
	v_mul_f32_e32 v137, v137, v184
	v_mul_f32_e32 v133, v133, v184
	v_mul_f32_e32 v134, 0xbfb8aa3b, v134
	v_mul_f32_e32 v130, 0xbfb8aa3b, v130
	v_mul_f32_e32 v135, 0xbfb8aa3b, v135
	v_mul_f32_e32 v131, 0xbfb8aa3b, v131
	v_mul_f32_e32 v136, 0xbfb8aa3b, v136
	v_mul_f32_e32 v132, 0xbfb8aa3b, v132
	v_mul_f32_e32 v137, 0xbfb8aa3b, v137
	v_mul_f32_e32 v133, 0xbfb8aa3b, v133
	v_exp_f32_e32 v134, v134
	v_exp_f32_e32 v130, v130
	v_exp_f32_e32 v135, v135
	v_exp_f32_e32 v131, v131
	v_exp_f32_e32 v136, v136
	v_exp_f32_e32 v132, v132
	v_exp_f32_e32 v137, v137
	v_exp_f32_e32 v133, v133
	v_add_f32_e32 v134, 1.0, v134
	v_add_f32_e32 v144, 1.0, v130
	v_add_f32_e32 v135, 1.0, v135
	v_add_f32_e32 v145, 1.0, v131
	v_add_f32_e32 v136, 1.0, v136
	v_add_f32_e32 v148, 1.0, v132
	v_add_f32_e32 v137, 1.0, v137
	v_add_f32_e32 v149, 1.0, v133
	v_rcp_f32_e32 v130, v134
	v_rcp_f32_e32 v132, v144
	v_rcp_f32_e32 v131, v135
	v_rcp_f32_e32 v133, v145
	v_rcp_f32_e32 v136, v136
	v_rcp_f32_e32 v144, v148
	v_rcp_f32_e32 v137, v137
	v_rcp_f32_e32 v145, v149
	s_lshl_b32 s11, s76, 2
	s_or_b32 s46, s11, s63
	s_ashr_i32 s47, s46, 31
	s_and_b64 vcc, exec, s[2:3]
	s_lshl_b64 s[46:47], s[46:47], 17
	s_waitcnt vmcnt(2)
	v_lshlrev_b32_e32 v134, 16, v140
	v_and_b32_e32 v135, 0xffff0000, v140
	v_lshlrev_b32_e32 v148, 16, v142
	v_and_b32_e32 v149, 0xffff0000, v142
	v_lshlrev_b32_e32 v140, 16, v141
	v_and_b32_e32 v141, 0xffff0000, v141
	v_lshlrev_b32_e32 v142, 16, v143
	v_and_b32_e32 v143, 0xffff0000, v143
	s_waitcnt vmcnt(1)
	v_pk_fma_f32 v[134:135], v[130:131], v[134:135], v[188:189]
	s_waitcnt vmcnt(0)
	v_pk_fma_f32 v[130:131], v[132:133], v[148:149], v[192:193]
	v_pk_fma_f32 v[136:137], v[136:137], v[140:141], v[190:191]
	v_pk_fma_f32 v[132:133], v[144:145], v[142:143], v[194:195]
	global_store_dwordx4 v[186:187], v[134:137], off offset:512 nt
	global_store_dwordx4 v[186:187], v[130:133], off offset:528 nt
	s_cbranch_vccnz .LBB0_981
	v_pk_mul_f32 v[140:141], v[56:57], v[136:137]
	v_pk_mul_f32 v[142:143], v[54:55], v[134:135]
	v_pk_mul_f32 v[134:135], v[134:135], v[134:135]
	v_pk_mul_f32 v[136:137], v[136:137], v[136:137]
	v_pk_mul_f32 v[148:149], v[130:131], v[130:131]
	v_add_f32_e32 v136, v136, v137
	v_add_f32_e32 v134, v134, v135
	v_pk_mul_f32 v[144:145], v[132:133], v[132:133]
	v_add_f32_e32 v134, v134, v136
	v_add_f32_e32 v135, v148, v149
	v_add_f32_e32 v134, v135, v134
	v_add_f32_e32 v135, v144, v145
	v_add_f32_e32 v134, v135, v134
	v_and_b32_e32 v135, 64, v207
	v_add_f32_e32 v144, v217, v134
	v_xor_b32_e32 v134, 16, v207
	v_add_u32_e32 v145, 64, v135
	v_cmp_lt_i32_e32 vcc, v134, v145
	v_pk_mul_f32 v[136:137], v[52:53], v[132:133]
	v_cvt_pk_bf16_f32 v132, v142, v143
	v_cndmask_b32_e32 v134, v207, v134, vcc
	v_lshlrev_b32_e32 v134, 2, v134
	ds_bpermute_b32 v148, v134, v144
	v_pk_mul_f32 v[134:135], v[50:51], v[130:131]
	v_xor_b32_e32 v131, 32, v207
	v_cmp_lt_i32_e32 vcc, v131, v145
	v_cvt_pk_bf16_f32 v133, v140, v141
	s_waitcnt lgkmcnt(0)
	v_add_f32_e32 v130, v144, v148
	v_cndmask_b32_e32 v131, v207, v131, vcc
	v_lshlrev_b32_e32 v131, 2, v131
	ds_bpermute_b32 v131, v131, v130
	v_cvt_pk_bf16_f32 v134, v134, v135
	v_cvt_pk_bf16_f32 v135, v136, v137
	v_lshl_add_u64 v[136:137], v[138:139], 1, s[30:31]
	global_store_dwordx4 v[136:137], v[132:135], off
	s_and_saveexec_b64 s[48:49], s[38:39]
	s_cbranch_execz .LBB0_980
	s_add_u32 s76, s28, s46
	s_addc_u32 s77, s29, s47
	v_lshl_add_u64 v[132:133], v[172:173], 2, s[76:77]
	s_waitcnt lgkmcnt(0)
	v_add_f32_e32 v130, v130, v131
	global_store_dword v[132:133], v130, off

.LBB0_981:
	s_nop 0
	v_or_b32_e32 v130, 16, v172
	s_waitcnt lgkmcnt(0)
	v_ashrrev_i32_e32 v131, 31, v130
	v_lshlrev_b64 v[130:131], 10, v[130:131]
	v_lshl_add_u64 v[130:131], v[130:131], 0, v[182:183]
	v_lshl_add_u64 v[132:133], v[130:131], 1, s[36:37]
	global_load_dwordx4 v[134:137], v[132:133], off
	v_lshl_add_u64 v[132:133], v[130:131], 2, s[16:17]
	global_load_dwordx4 v[138:141], v[132:133], off
	global_load_dwordx4 v[142:145], v[132:133], off offset:16
	v_mul_f32_e32 v126, v126, v185
	v_mul_f32_e32 v122, v122, v185
	v_mul_f32_e32 v127, v127, v185
	v_mul_f32_e32 v123, v123, v185
	v_mul_f32_e32 v128, v128, v185
	v_mul_f32_e32 v124, v124, v185
	v_mul_f32_e32 v129, v129, v185
	v_mul_f32_e32 v125, v125, v185
	v_mul_f32_e32 v126, 0xbfb8aa3b, v126
	v_mul_f32_e32 v122, 0xbfb8aa3b, v122
	v_mul_f32_e32 v127, 0xbfb8aa3b, v127
	v_mul_f32_e32 v123, 0xbfb8aa3b, v123
	v_mul_f32_e32 v128, 0xbfb8aa3b, v128
	v_mul_f32_e32 v124, 0xbfb8aa3b, v124
	v_mul_f32_e32 v129, 0xbfb8aa3b, v129
	v_mul_f32_e32 v125, 0xbfb8aa3b, v125
	v_exp_f32_e32 v126, v126
	v_exp_f32_e32 v122, v122
	v_exp_f32_e32 v127, v127
	v_exp_f32_e32 v123, v123
	v_exp_f32_e32 v128, v128
	v_exp_f32_e32 v124, v124
	v_exp_f32_e32 v129, v129
	v_exp_f32_e32 v125, v125
	v_add_f32_e32 v126, 1.0, v126
	v_add_f32_e32 v148, 1.0, v122
	v_add_f32_e32 v127, 1.0, v127
	v_add_f32_e32 v123, 1.0, v123
	v_add_f32_e32 v149, 1.0, v128
	v_add_f32_e32 v184, 1.0, v124
	v_add_f32_e32 v129, 1.0, v129
	v_add_f32_e32 v186, 1.0, v125
	v_rcp_f32_e32 v122, v126
	v_rcp_f32_e32 v124, v148
	v_rcp_f32_e32 v126, v127
	v_rcp_f32_e32 v128, v123
	v_rcp_f32_e32 v123, v149
	v_rcp_f32_e32 v125, v184
	v_rcp_f32_e32 v127, v129
	v_rcp_f32_e32 v129, v186
	s_and_b64 vcc, exec, s[2:3]
	s_waitcnt vmcnt(2)
	v_lshlrev_b32_e32 v149, 16, v135
	v_lshlrev_b32_e32 v148, 16, v134
	v_and_b32_e32 v187, 0xffff0000, v135
	v_and_b32_e32 v186, 0xffff0000, v134
	s_waitcnt vmcnt(1)
	v_mov_b32_e32 v134, v138
	v_mov_b32_e32 v135, v140
	v_mov_b32_e32 v140, v139
	v_lshlrev_b32_e32 v189, 16, v137
	v_lshlrev_b32_e32 v188, 16, v136
	v_and_b32_e32 v191, 0xffff0000, v137
	v_and_b32_e32 v190, 0xffff0000, v136
	s_waitcnt vmcnt(0)
	v_mov_b32_e32 v136, v142
	v_mov_b32_e32 v137, v144
	v_mov_b32_e32 v144, v143
	v_pk_fma_f32 v[134:135], v[122:123], v[148:149], v[134:135]
	v_pk_fma_f32 v[138:139], v[126:127], v[186:187], v[140:141]
	v_pk_fma_f32 v[136:137], v[124:125], v[188:189], v[136:137]
	v_pk_fma_f32 v[140:141], v[128:129], v[190:191], v[144:145]
	v_mov_b32_e32 v126, v134
	v_mov_b32_e32 v127, v138
	v_mov_b32_e32 v128, v135
	v_mov_b32_e32 v129, v139
	v_mov_b32_e32 v122, v136
	v_mov_b32_e32 v123, v140
	v_mov_b32_e32 v124, v137
	v_mov_b32_e32 v125, v141
	v_mov_b32_e32 v142, 0
	global_store_dwordx4 v[132:133], v[126:129], off nt
	global_store_dwordx4 v[132:133], v[122:125], off offset:16 nt
	s_cbranch_vccnz .LBB0_983
	v_pk_mul_f32 v[138:139], v[138:139], v[138:139]
	v_pk_mul_f32 v[128:129], v[64:65], v[128:129]
	v_pk_fma_f32 v[134:135], v[134:135], v[134:135], v[138:139]
	v_pk_mul_f32 v[138:139], v[140:141], v[140:141]
	v_add_f32_e32 v134, v134, v135
	v_pk_fma_f32 v[136:137], v[136:137], v[136:137], v[138:139]
	v_pk_mul_f32 v[126:127], v[62:63], v[126:127]
	v_add_f32_e32 v134, v136, v134
	v_add_f32_e32 v142, v137, v134
	v_pk_mul_f32 v[134:135], v[60:61], v[124:125]
	v_pk_mul_f32 v[124:125], v[58:59], v[122:123]
	v_cvt_pk_bf16_f32 v122, v126, v127
	v_cvt_pk_bf16_f32 v123, v128, v129
	v_cvt_pk_bf16_f32 v124, v124, v125
	v_cvt_pk_bf16_f32 v125, v134, v135
	v_lshl_add_u64 v[126:127], v[130:131], 1, s[30:31]
	global_store_dwordx4 v[126:127], v[122:125], off
.LBB0_983:
	v_or_b32_e32 v130, 0x80, v130
	s_nop 0
	v_lshl_add_u64 v[122:123], v[130:131], 1, s[36:37]
	global_load_dwordx4 v[122:125], v[122:123], off
	s_nop 0
	global_load_dwordx4 v[126:129], v[132:133], off offset:512
	global_load_dwordx4 v[134:137], v[132:133], off offset:528
	v_mul_f32_e32 v118, v118, v185
	v_mul_f32_e32 v114, v114, v185
	v_mul_f32_e32 v119, v119, v185
	v_mul_f32_e32 v115, v115, v185
	v_mul_f32_e32 v120, v120, v185
	v_mul_f32_e32 v116, v116, v185
	v_mul_f32_e32 v121, v121, v185
	v_mul_f32_e32 v117, v117, v185
	v_mul_f32_e32 v118, 0xbfb8aa3b, v118
	v_mul_f32_e32 v114, 0xbfb8aa3b, v114
	v_mul_f32_e32 v119, 0xbfb8aa3b, v119
	v_mul_f32_e32 v115, 0xbfb8aa3b, v115
	v_mul_f32_e32 v120, 0xbfb8aa3b, v120
	v_mul_f32_e32 v116, 0xbfb8aa3b, v116
	v_mul_f32_e32 v121, 0xbfb8aa3b, v121
	v_mul_f32_e32 v117, 0xbfb8aa3b, v117
	v_exp_f32_e32 v118, v118
	v_exp_f32_e32 v114, v114
	v_exp_f32_e32 v119, v119
	v_exp_f32_e32 v115, v115
	v_exp_f32_e32 v120, v120
	v_exp_f32_e32 v116, v116
	v_exp_f32_e32 v121, v121
	v_exp_f32_e32 v117, v117
	v_add_f32_e32 v118, 1.0, v118
	v_add_f32_e32 v138, 1.0, v114
	v_add_f32_e32 v119, 1.0, v119
	v_add_f32_e32 v139, 1.0, v115
	v_add_f32_e32 v120, 1.0, v120
	v_add_f32_e32 v140, 1.0, v116
	v_add_f32_e32 v121, 1.0, v121
	v_add_f32_e32 v141, 1.0, v117
	v_rcp_f32_e32 v114, v118
	v_rcp_f32_e32 v116, v138
	v_rcp_f32_e32 v115, v119
	v_rcp_f32_e32 v117, v139
	v_rcp_f32_e32 v120, v120
	v_rcp_f32_e32 v138, v140
	v_rcp_f32_e32 v121, v121
	v_rcp_f32_e32 v139, v141
	s_and_b64 vcc, exec, s[2:3]
	s_waitcnt vmcnt(2)
	v_lshlrev_b32_e32 v118, 16, v122
	v_and_b32_e32 v119, 0xffff0000, v122
	v_lshlrev_b32_e32 v140, 16, v124
	v_and_b32_e32 v141, 0xffff0000, v124
	v_lshlrev_b32_e32 v122, 16, v123
	v_and_b32_e32 v123, 0xffff0000, v123
	v_lshlrev_b32_e32 v124, 16, v125
	v_and_b32_e32 v125, 0xffff0000, v125
	s_waitcnt vmcnt(1)
	v_pk_fma_f32 v[118:119], v[114:115], v[118:119], v[126:127]
	s_waitcnt vmcnt(0)
	v_pk_fma_f32 v[114:115], v[116:117], v[140:141], v[134:135]
	v_pk_fma_f32 v[120:121], v[120:121], v[122:123], v[128:129]
	v_pk_fma_f32 v[116:117], v[138:139], v[124:125], v[136:137]
	global_store_dwordx4 v[132:133], v[118:121], off offset:512 nt
	global_store_dwordx4 v[132:133], v[114:117], off offset:528 nt
	s_cbranch_vccnz .LBB0_987
	v_pk_mul_f32 v[122:123], v[56:57], v[120:121]
	v_pk_mul_f32 v[124:125], v[54:55], v[118:119]
	v_pk_mul_f32 v[118:119], v[118:119], v[118:119]
	v_pk_mul_f32 v[120:121], v[120:121], v[120:121]
	v_pk_mul_f32 v[128:129], v[114:115], v[114:115]
	v_add_f32_e32 v120, v120, v121
	v_add_f32_e32 v118, v118, v119
	v_pk_mul_f32 v[126:127], v[116:117], v[116:117]
	v_add_f32_e32 v118, v118, v120
	v_add_f32_e32 v119, v128, v129
	v_add_f32_e32 v118, v119, v118
	v_add_f32_e32 v119, v126, v127
	v_add_f32_e32 v118, v119, v118
	v_and_b32_e32 v119, 64, v207
	v_add_f32_e32 v126, v142, v118
	v_xor_b32_e32 v118, 16, v207
	v_add_u32_e32 v127, 64, v119
	v_cmp_lt_i32_e32 vcc, v118, v127
	v_pk_mul_f32 v[120:121], v[52:53], v[116:117]
	v_cvt_pk_bf16_f32 v116, v124, v125
	v_cndmask_b32_e32 v118, v207, v118, vcc
	v_lshlrev_b32_e32 v118, 2, v118
	ds_bpermute_b32 v128, v118, v126
	v_pk_mul_f32 v[118:119], v[50:51], v[114:115]
	v_xor_b32_e32 v115, 32, v207
	v_cmp_lt_i32_e32 vcc, v115, v127
	v_cvt_pk_bf16_f32 v117, v122, v123
	s_waitcnt lgkmcnt(0)
	v_add_f32_e32 v114, v126, v128
	v_cndmask_b32_e32 v115, v207, v115, vcc
	v_lshlrev_b32_e32 v115, 2, v115
	ds_bpermute_b32 v115, v115, v114
	v_cvt_pk_bf16_f32 v118, v118, v119
	v_cvt_pk_bf16_f32 v119, v120, v121
	v_lshl_add_u64 v[120:121], v[130:131], 1, s[30:31]
	global_store_dwordx4 v[120:121], v[116:119], off
	s_and_saveexec_b64 s[48:49], s[38:39]
	s_cbranch_execz .LBB0_986
	s_add_u32 s76, s28, s46
	s_addc_u32 s77, s29, s47
	v_lshl_add_u64 v[116:117], v[172:173], 2, s[76:77]
	s_waitcnt lgkmcnt(0)
	v_add_f32_e32 v114, v114, v115
	global_store_dword v[116:117], v114, off offset:64

.LBB0_987:
	s_nop 0
	v_or_b32_e32 v114, 32, v172
	s_waitcnt lgkmcnt(0)
	v_ashrrev_i32_e32 v115, 31, v114
	v_lshlrev_b64 v[114:115], 10, v[114:115]
	v_lshl_add_u64 v[114:115], v[114:115], 0, v[182:183]
	v_lshl_add_u64 v[116:117], v[114:115], 1, s[36:37]
	global_load_dwordx4 v[118:121], v[116:117], off
	v_lshl_add_u64 v[116:117], v[114:115], 2, s[16:17]
	global_load_dwordx4 v[122:125], v[116:117], off
	global_load_dwordx4 v[126:129], v[116:117], off offset:16
	v_mul_f32_e32 v110, v110, v180
	v_mul_f32_e32 v106, v106, v180
	v_mul_f32_e32 v111, v111, v180
	v_mul_f32_e32 v107, v107, v180
	v_mul_f32_e32 v112, v112, v180
	v_mul_f32_e32 v108, v108, v180
	v_mul_f32_e32 v113, v113, v180
	v_mul_f32_e32 v109, v109, v180
	v_mul_f32_e32 v110, 0xbfb8aa3b, v110
	v_mul_f32_e32 v106, 0xbfb8aa3b, v106
	v_mul_f32_e32 v111, 0xbfb8aa3b, v111
	v_mul_f32_e32 v107, 0xbfb8aa3b, v107
	v_mul_f32_e32 v112, 0xbfb8aa3b, v112
	v_mul_f32_e32 v108, 0xbfb8aa3b, v108
	v_mul_f32_e32 v113, 0xbfb8aa3b, v113
	v_mul_f32_e32 v109, 0xbfb8aa3b, v109
	v_exp_f32_e32 v110, v110
	v_exp_f32_e32 v106, v106
	v_exp_f32_e32 v111, v111
	v_exp_f32_e32 v107, v107
	v_exp_f32_e32 v112, v112
	v_exp_f32_e32 v108, v108
	v_exp_f32_e32 v113, v113
	v_exp_f32_e32 v109, v109
	v_add_f32_e32 v110, 1.0, v110
	v_add_f32_e32 v130, 1.0, v106
	v_add_f32_e32 v111, 1.0, v111
	v_add_f32_e32 v107, 1.0, v107
	v_add_f32_e32 v131, 1.0, v112
	v_add_f32_e32 v132, 1.0, v108
	v_add_f32_e32 v113, 1.0, v113
	v_add_f32_e32 v133, 1.0, v109
	v_rcp_f32_e32 v106, v110
	v_rcp_f32_e32 v108, v130
	v_rcp_f32_e32 v110, v111
	v_rcp_f32_e32 v112, v107
	v_rcp_f32_e32 v107, v131
	v_rcp_f32_e32 v109, v132
	v_rcp_f32_e32 v111, v113
	v_rcp_f32_e32 v113, v133
	s_and_b64 vcc, exec, s[2:3]
	s_waitcnt vmcnt(2)
	v_lshlrev_b32_e32 v131, 16, v119
	v_lshlrev_b32_e32 v130, 16, v118
	v_and_b32_e32 v133, 0xffff0000, v119
	v_and_b32_e32 v132, 0xffff0000, v118
	s_waitcnt vmcnt(1)
	v_mov_b32_e32 v118, v122
	v_mov_b32_e32 v119, v124
	v_mov_b32_e32 v124, v123
	v_lshlrev_b32_e32 v135, 16, v121
	v_lshlrev_b32_e32 v134, 16, v120
	v_and_b32_e32 v137, 0xffff0000, v121
	v_and_b32_e32 v136, 0xffff0000, v120
	s_waitcnt vmcnt(0)
	v_mov_b32_e32 v120, v126
	v_mov_b32_e32 v121, v128
	v_mov_b32_e32 v128, v127
	v_pk_fma_f32 v[118:119], v[106:107], v[130:131], v[118:119]
	v_pk_fma_f32 v[122:123], v[110:111], v[132:133], v[124:125]
	v_pk_fma_f32 v[120:121], v[108:109], v[134:135], v[120:121]
	v_pk_fma_f32 v[124:125], v[112:113], v[136:137], v[128:129]
	v_mov_b32_e32 v110, v118
	v_mov_b32_e32 v111, v122
	v_mov_b32_e32 v112, v119
	v_mov_b32_e32 v113, v123
	v_mov_b32_e32 v106, v120
	v_mov_b32_e32 v107, v124
	v_mov_b32_e32 v108, v121
	v_mov_b32_e32 v109, v125
	v_mov_b32_e32 v126, 0
	global_store_dwordx4 v[116:117], v[110:113], off nt
	global_store_dwordx4 v[116:117], v[106:109], off offset:16 nt
	s_cbranch_vccnz .LBB0_989
	v_pk_mul_f32 v[122:123], v[122:123], v[122:123]
	v_pk_mul_f32 v[112:113], v[64:65], v[112:113]
	v_pk_fma_f32 v[118:119], v[118:119], v[118:119], v[122:123]
	v_pk_mul_f32 v[122:123], v[124:125], v[124:125]
	v_add_f32_e32 v118, v118, v119
	v_pk_fma_f32 v[120:121], v[120:121], v[120:121], v[122:123]
	v_pk_mul_f32 v[110:111], v[62:63], v[110:111]
	v_add_f32_e32 v118, v120, v118
	v_add_f32_e32 v126, v121, v118
	v_pk_mul_f32 v[118:119], v[60:61], v[108:109]
	v_pk_mul_f32 v[108:109], v[58:59], v[106:107]
	v_cvt_pk_bf16_f32 v106, v110, v111
	v_cvt_pk_bf16_f32 v107, v112, v113
	v_cvt_pk_bf16_f32 v108, v108, v109
	v_cvt_pk_bf16_f32 v109, v118, v119
	v_lshl_add_u64 v[110:111], v[114:115], 1, s[30:31]
	global_store_dwordx4 v[110:111], v[106:109], off
.LBB0_989:
	v_or_b32_e32 v114, 0x80, v114
	s_nop 0
	v_lshl_add_u64 v[106:107], v[114:115], 1, s[36:37]
	global_load_dwordx4 v[106:109], v[106:107], off
	s_nop 0
	global_load_dwordx4 v[110:113], v[116:117], off offset:512
	global_load_dwordx4 v[118:121], v[116:117], off offset:528
	v_mul_f32_e32 v102, v102, v180
	v_mul_f32_e32 v98, v98, v180
	v_mul_f32_e32 v103, v103, v180
	v_mul_f32_e32 v99, v99, v180
	v_mul_f32_e32 v104, v104, v180
	v_mul_f32_e32 v100, v100, v180
	v_mul_f32_e32 v105, v105, v180
	v_mul_f32_e32 v101, v101, v180
	v_mul_f32_e32 v102, 0xbfb8aa3b, v102
	v_mul_f32_e32 v98, 0xbfb8aa3b, v98
	v_mul_f32_e32 v103, 0xbfb8aa3b, v103
	v_mul_f32_e32 v99, 0xbfb8aa3b, v99
	v_mul_f32_e32 v104, 0xbfb8aa3b, v104
	v_mul_f32_e32 v100, 0xbfb8aa3b, v100
	v_mul_f32_e32 v105, 0xbfb8aa3b, v105
	v_mul_f32_e32 v101, 0xbfb8aa3b, v101
	v_exp_f32_e32 v102, v102
	v_exp_f32_e32 v98, v98
	v_exp_f32_e32 v103, v103
	v_exp_f32_e32 v99, v99
	v_exp_f32_e32 v104, v104
	v_exp_f32_e32 v100, v100
	v_exp_f32_e32 v105, v105
	v_exp_f32_e32 v101, v101
	v_add_f32_e32 v102, 1.0, v102
	v_add_f32_e32 v122, 1.0, v98
	v_add_f32_e32 v103, 1.0, v103
	v_add_f32_e32 v123, 1.0, v99
	v_add_f32_e32 v104, 1.0, v104
	v_add_f32_e32 v124, 1.0, v100
	v_add_f32_e32 v105, 1.0, v105
	v_add_f32_e32 v125, 1.0, v101
	v_rcp_f32_e32 v98, v102
	v_rcp_f32_e32 v100, v122
	v_rcp_f32_e32 v99, v103
	v_rcp_f32_e32 v101, v123
	v_rcp_f32_e32 v104, v104
	v_rcp_f32_e32 v122, v124
	v_rcp_f32_e32 v105, v105
	v_rcp_f32_e32 v123, v125
	s_and_b64 vcc, exec, s[2:3]
	s_waitcnt vmcnt(2)
	v_lshlrev_b32_e32 v102, 16, v106
	v_and_b32_e32 v103, 0xffff0000, v106
	v_lshlrev_b32_e32 v124, 16, v108
	v_and_b32_e32 v125, 0xffff0000, v108
	v_lshlrev_b32_e32 v106, 16, v107
	v_and_b32_e32 v107, 0xffff0000, v107
	v_lshlrev_b32_e32 v108, 16, v109
	v_and_b32_e32 v109, 0xffff0000, v109
	s_waitcnt vmcnt(1)
	v_pk_fma_f32 v[102:103], v[98:99], v[102:103], v[110:111]
	s_waitcnt vmcnt(0)
	v_pk_fma_f32 v[98:99], v[100:101], v[124:125], v[118:119]
	v_pk_fma_f32 v[104:105], v[104:105], v[106:107], v[112:113]
	v_pk_fma_f32 v[100:101], v[122:123], v[108:109], v[120:121]
	global_store_dwordx4 v[116:117], v[102:105], off offset:512 nt
	global_store_dwordx4 v[116:117], v[98:101], off offset:528 nt
	s_cbranch_vccnz .LBB0_993
	v_pk_mul_f32 v[106:107], v[56:57], v[104:105]
	v_pk_mul_f32 v[108:109], v[54:55], v[102:103]
	v_pk_mul_f32 v[102:103], v[102:103], v[102:103]
	v_pk_mul_f32 v[104:105], v[104:105], v[104:105]
	v_pk_mul_f32 v[112:113], v[98:99], v[98:99]
	v_add_f32_e32 v104, v104, v105
	v_add_f32_e32 v102, v102, v103
	v_pk_mul_f32 v[110:111], v[100:101], v[100:101]
	v_add_f32_e32 v102, v102, v104
	v_add_f32_e32 v103, v112, v113
	v_add_f32_e32 v102, v103, v102
	v_add_f32_e32 v103, v110, v111
	v_add_f32_e32 v102, v103, v102
	v_and_b32_e32 v103, 64, v207
	v_add_f32_e32 v110, v126, v102
	v_xor_b32_e32 v102, 16, v207
	v_add_u32_e32 v111, 64, v103
	v_cmp_lt_i32_e32 vcc, v102, v111
	v_pk_mul_f32 v[104:105], v[52:53], v[100:101]
	v_cvt_pk_bf16_f32 v100, v108, v109
	v_cndmask_b32_e32 v102, v207, v102, vcc
	v_lshlrev_b32_e32 v102, 2, v102
	ds_bpermute_b32 v112, v102, v110
	v_pk_mul_f32 v[102:103], v[50:51], v[98:99]
	v_xor_b32_e32 v99, 32, v207
	v_cmp_lt_i32_e32 vcc, v99, v111
	v_cvt_pk_bf16_f32 v101, v106, v107
	s_waitcnt lgkmcnt(0)
	v_add_f32_e32 v98, v110, v112
	v_cndmask_b32_e32 v99, v207, v99, vcc
	v_lshlrev_b32_e32 v99, 2, v99
	ds_bpermute_b32 v99, v99, v98
	v_cvt_pk_bf16_f32 v102, v102, v103
	v_cvt_pk_bf16_f32 v103, v104, v105
	v_lshl_add_u64 v[104:105], v[114:115], 1, s[30:31]
	global_store_dwordx4 v[104:105], v[100:103], off
	s_and_saveexec_b64 s[48:49], s[38:39]
	s_cbranch_execz .LBB0_992
	s_add_u32 s76, s28, s46
	s_addc_u32 s77, s29, s47
	v_lshl_add_u64 v[100:101], v[172:173], 2, s[76:77]
	s_waitcnt lgkmcnt(0)
	v_add_f32_e32 v98, v98, v99
	global_store_dword v[100:101], v98, off offset:128

.LBB0_993:
	s_nop 0
	v_or_b32_e32 v98, 48, v172
	s_waitcnt lgkmcnt(0)
	v_ashrrev_i32_e32 v99, 31, v98
	v_lshlrev_b64 v[98:99], 10, v[98:99]
	v_lshl_add_u64 v[98:99], v[98:99], 0, v[182:183]
	v_lshl_add_u64 v[100:101], v[98:99], 1, s[36:37]
	global_load_dwordx4 v[102:105], v[100:101], off
	v_lshl_add_u64 v[100:101], v[98:99], 2, s[16:17]
	global_load_dwordx4 v[106:109], v[100:101], off
	global_load_dwordx4 v[110:113], v[100:101], off offset:16
	v_mul_f32_e32 v94, v94, v181
	v_mul_f32_e32 v90, v90, v181
	v_mul_f32_e32 v95, v95, v181
	v_mul_f32_e32 v91, v91, v181
	v_mul_f32_e32 v96, v96, v181
	v_mul_f32_e32 v92, v92, v181
	v_mul_f32_e32 v97, v97, v181
	v_mul_f32_e32 v93, v93, v181
	v_mul_f32_e32 v94, 0xbfb8aa3b, v94
	v_mul_f32_e32 v90, 0xbfb8aa3b, v90
	v_mul_f32_e32 v95, 0xbfb8aa3b, v95
	v_mul_f32_e32 v91, 0xbfb8aa3b, v91
	v_mul_f32_e32 v96, 0xbfb8aa3b, v96
	v_mul_f32_e32 v92, 0xbfb8aa3b, v92
	v_mul_f32_e32 v97, 0xbfb8aa3b, v97
	v_mul_f32_e32 v93, 0xbfb8aa3b, v93
	v_exp_f32_e32 v94, v94
	v_exp_f32_e32 v90, v90
	v_exp_f32_e32 v95, v95
	v_exp_f32_e32 v91, v91
	v_exp_f32_e32 v96, v96
	v_exp_f32_e32 v92, v92
	v_exp_f32_e32 v97, v97
	v_exp_f32_e32 v93, v93
	v_add_f32_e32 v94, 1.0, v94
	v_add_f32_e32 v114, 1.0, v90
	v_add_f32_e32 v95, 1.0, v95
	v_add_f32_e32 v91, 1.0, v91
	v_add_f32_e32 v115, 1.0, v96
	v_add_f32_e32 v116, 1.0, v92
	v_add_f32_e32 v97, 1.0, v97
	v_add_f32_e32 v117, 1.0, v93
	v_rcp_f32_e32 v90, v94
	v_rcp_f32_e32 v92, v114
	v_rcp_f32_e32 v94, v95
	v_rcp_f32_e32 v96, v91
	v_rcp_f32_e32 v91, v115
	v_rcp_f32_e32 v93, v116
	v_rcp_f32_e32 v95, v97
	v_rcp_f32_e32 v97, v117
	s_and_b64 vcc, exec, s[2:3]
	s_waitcnt vmcnt(2)
	v_lshlrev_b32_e32 v115, 16, v103
	v_lshlrev_b32_e32 v114, 16, v102
	v_and_b32_e32 v117, 0xffff0000, v103
	v_and_b32_e32 v116, 0xffff0000, v102
	s_waitcnt vmcnt(1)
	v_mov_b32_e32 v102, v106
	v_mov_b32_e32 v103, v108
	v_mov_b32_e32 v108, v107
	v_lshlrev_b32_e32 v119, 16, v105
	v_lshlrev_b32_e32 v118, 16, v104
	v_and_b32_e32 v121, 0xffff0000, v105
	v_and_b32_e32 v120, 0xffff0000, v104
	s_waitcnt vmcnt(0)
	v_mov_b32_e32 v104, v110
	v_mov_b32_e32 v105, v112
	v_mov_b32_e32 v112, v111
	v_pk_fma_f32 v[102:103], v[90:91], v[114:115], v[102:103]
	v_pk_fma_f32 v[106:107], v[94:95], v[116:117], v[108:109]
	v_pk_fma_f32 v[104:105], v[92:93], v[118:119], v[104:105]
	v_pk_fma_f32 v[108:109], v[96:97], v[120:121], v[112:113]
	v_mov_b32_e32 v94, v102
	v_mov_b32_e32 v95, v106
	v_mov_b32_e32 v96, v103
	v_mov_b32_e32 v97, v107
	v_mov_b32_e32 v90, v104
	v_mov_b32_e32 v91, v108
	v_mov_b32_e32 v92, v105
	v_mov_b32_e32 v93, v109
	v_mov_b32_e32 v110, 0
	global_store_dwordx4 v[100:101], v[94:97], off nt
	global_store_dwordx4 v[100:101], v[90:93], off offset:16 nt
	s_cbranch_vccnz .LBB0_995
	v_pk_mul_f32 v[106:107], v[106:107], v[106:107]
	v_pk_mul_f32 v[96:97], v[64:65], v[96:97]
	v_pk_fma_f32 v[102:103], v[102:103], v[102:103], v[106:107]
	v_pk_mul_f32 v[106:107], v[108:109], v[108:109]
	v_add_f32_e32 v102, v102, v103
	v_pk_fma_f32 v[104:105], v[104:105], v[104:105], v[106:107]
	v_pk_mul_f32 v[94:95], v[62:63], v[94:95]
	v_add_f32_e32 v102, v104, v102
	v_add_f32_e32 v110, v105, v102
	v_pk_mul_f32 v[102:103], v[60:61], v[92:93]
	v_pk_mul_f32 v[92:93], v[58:59], v[90:91]
	v_cvt_pk_bf16_f32 v90, v94, v95
	v_cvt_pk_bf16_f32 v91, v96, v97
	v_cvt_pk_bf16_f32 v92, v92, v93
	v_cvt_pk_bf16_f32 v93, v102, v103
	v_lshl_add_u64 v[94:95], v[98:99], 1, s[30:31]
	global_store_dwordx4 v[94:95], v[90:93], off
.LBB0_995:
	v_or_b32_e32 v98, 0x80, v98
	s_nop 0
	v_lshl_add_u64 v[90:91], v[98:99], 1, s[36:37]
	global_load_dwordx4 v[90:93], v[90:91], off
	s_nop 0
	global_load_dwordx4 v[94:97], v[100:101], off offset:512
	global_load_dwordx4 v[102:105], v[100:101], off offset:528
	v_mul_f32_e32 v86, v86, v181
	v_mul_f32_e32 v82, v82, v181
	v_mul_f32_e32 v87, v87, v181
	v_mul_f32_e32 v83, v83, v181
	v_mul_f32_e32 v88, v88, v181
	v_mul_f32_e32 v84, v84, v181
	v_mul_f32_e32 v89, v89, v181
	v_mul_f32_e32 v85, v85, v181
	v_mul_f32_e32 v86, 0xbfb8aa3b, v86
	v_mul_f32_e32 v82, 0xbfb8aa3b, v82
	v_mul_f32_e32 v87, 0xbfb8aa3b, v87
	v_mul_f32_e32 v83, 0xbfb8aa3b, v83
	v_mul_f32_e32 v88, 0xbfb8aa3b, v88
	v_mul_f32_e32 v84, 0xbfb8aa3b, v84
	v_mul_f32_e32 v89, 0xbfb8aa3b, v89
	v_mul_f32_e32 v85, 0xbfb8aa3b, v85
	v_exp_f32_e32 v86, v86
	v_exp_f32_e32 v82, v82
	v_exp_f32_e32 v87, v87
	v_exp_f32_e32 v83, v83
	v_exp_f32_e32 v88, v88
	v_exp_f32_e32 v84, v84
	v_exp_f32_e32 v89, v89
	v_exp_f32_e32 v85, v85
	v_add_f32_e32 v86, 1.0, v86
	v_add_f32_e32 v106, 1.0, v82
	v_add_f32_e32 v87, 1.0, v87
	v_add_f32_e32 v107, 1.0, v83
	v_add_f32_e32 v88, 1.0, v88
	v_add_f32_e32 v108, 1.0, v84
	v_add_f32_e32 v89, 1.0, v89
	v_add_f32_e32 v109, 1.0, v85
	v_rcp_f32_e32 v82, v86
	v_rcp_f32_e32 v84, v106
	v_rcp_f32_e32 v83, v87
	v_rcp_f32_e32 v85, v107
	v_rcp_f32_e32 v88, v88
	v_rcp_f32_e32 v106, v108
	v_rcp_f32_e32 v89, v89
	v_rcp_f32_e32 v107, v109
	s_and_b64 vcc, exec, s[2:3]
	s_waitcnt vmcnt(2)
	v_lshlrev_b32_e32 v86, 16, v90
	v_and_b32_e32 v87, 0xffff0000, v90
	v_lshlrev_b32_e32 v108, 16, v92
	v_and_b32_e32 v109, 0xffff0000, v92
	v_lshlrev_b32_e32 v90, 16, v91
	v_and_b32_e32 v91, 0xffff0000, v91
	v_lshlrev_b32_e32 v92, 16, v93
	v_and_b32_e32 v93, 0xffff0000, v93
	s_waitcnt vmcnt(1)
	v_pk_fma_f32 v[86:87], v[82:83], v[86:87], v[94:95]
	s_waitcnt vmcnt(0)
	v_pk_fma_f32 v[82:83], v[84:85], v[108:109], v[102:103]
	v_pk_fma_f32 v[88:89], v[88:89], v[90:91], v[96:97]
	v_pk_fma_f32 v[84:85], v[106:107], v[92:93], v[104:105]
	global_store_dwordx4 v[100:101], v[86:89], off offset:512 nt
	global_store_dwordx4 v[100:101], v[82:85], off offset:528 nt
	s_cbranch_vccnz .LBB0_999
	v_pk_mul_f32 v[90:91], v[56:57], v[88:89]
	v_pk_mul_f32 v[92:93], v[54:55], v[86:87]
	v_pk_mul_f32 v[86:87], v[86:87], v[86:87]
	v_pk_mul_f32 v[88:89], v[88:89], v[88:89]
	v_pk_mul_f32 v[96:97], v[82:83], v[82:83]
	v_add_f32_e32 v88, v88, v89
	v_add_f32_e32 v86, v86, v87
	v_pk_mul_f32 v[94:95], v[84:85], v[84:85]
	v_add_f32_e32 v86, v86, v88
	v_add_f32_e32 v87, v96, v97
	v_add_f32_e32 v86, v87, v86
	v_add_f32_e32 v87, v94, v95
	v_add_f32_e32 v86, v87, v86
	v_and_b32_e32 v87, 64, v207
	v_add_f32_e32 v94, v110, v86
	v_xor_b32_e32 v86, 16, v207
	v_add_u32_e32 v95, 64, v87
	v_cmp_lt_i32_e32 vcc, v86, v95
	v_pk_mul_f32 v[88:89], v[52:53], v[84:85]
	v_cvt_pk_bf16_f32 v84, v92, v93
	v_cndmask_b32_e32 v86, v207, v86, vcc
	v_lshlrev_b32_e32 v86, 2, v86
	ds_bpermute_b32 v96, v86, v94
	v_pk_mul_f32 v[86:87], v[50:51], v[82:83]
	v_xor_b32_e32 v83, 32, v207
	v_cmp_lt_i32_e32 vcc, v83, v95
	v_cvt_pk_bf16_f32 v85, v90, v91
	s_waitcnt lgkmcnt(0)
	v_add_f32_e32 v82, v94, v96
	v_cndmask_b32_e32 v83, v207, v83, vcc
	v_lshlrev_b32_e32 v83, 2, v83
	ds_bpermute_b32 v83, v83, v82
	v_cvt_pk_bf16_f32 v86, v86, v87
	v_cvt_pk_bf16_f32 v87, v88, v89
	v_lshl_add_u64 v[88:89], v[98:99], 1, s[30:31]
	global_store_dwordx4 v[88:89], v[84:87], off
	s_and_saveexec_b64 s[48:49], s[38:39]
	s_cbranch_execz .LBB0_998
	s_add_u32 s76, s28, s46
	s_addc_u32 s77, s29, s47
	v_lshl_add_u64 v[84:85], v[172:173], 2, s[76:77]
	s_waitcnt lgkmcnt(0)
	v_add_f32_e32 v82, v82, v83
	global_store_dword v[84:85], v82, off offset:192

.LBB0_999:
	s_mov_b64 s[48:49], 0x20000
	s_waitcnt lgkmcnt(0)
	v_lshl_add_u64 v[82:83], v[176:177], 0, s[48:49]
	v_lshl_add_u64 v[84:85], v[82:83], 1, s[36:37]
	global_load_dwordx4 v[86:89], v[84:85], off
	v_lshl_add_u64 v[84:85], v[82:83], 2, s[16:17]
	global_load_dwordx4 v[90:93], v[84:85], off
	global_load_dwordx4 v[94:97], v[84:85], off offset:16
	v_mul_f32_e32 v78, v78, v178
	v_mul_f32_e32 v74, v74, v178
	v_mul_f32_e32 v79, v79, v178
	v_mul_f32_e32 v75, v75, v178
	v_mul_f32_e32 v80, v80, v178
	v_mul_f32_e32 v76, v76, v178
	v_mul_f32_e32 v81, v81, v178
	v_mul_f32_e32 v77, v77, v178
	v_mul_f32_e32 v78, 0xbfb8aa3b, v78
	v_mul_f32_e32 v74, 0xbfb8aa3b, v74
	v_mul_f32_e32 v79, 0xbfb8aa3b, v79
	v_mul_f32_e32 v75, 0xbfb8aa3b, v75
	v_mul_f32_e32 v80, 0xbfb8aa3b, v80
	v_mul_f32_e32 v76, 0xbfb8aa3b, v76
	v_mul_f32_e32 v81, 0xbfb8aa3b, v81
	v_mul_f32_e32 v77, 0xbfb8aa3b, v77
	v_exp_f32_e32 v78, v78
	v_exp_f32_e32 v74, v74
	v_exp_f32_e32 v79, v79
	v_exp_f32_e32 v75, v75
	v_exp_f32_e32 v80, v80
	v_exp_f32_e32 v76, v76
	v_exp_f32_e32 v81, v81
	v_exp_f32_e32 v77, v77
	v_add_f32_e32 v78, 1.0, v78
	v_add_f32_e32 v98, 1.0, v74
	v_add_f32_e32 v79, 1.0, v79
	v_add_f32_e32 v75, 1.0, v75
	v_add_f32_e32 v99, 1.0, v80
	v_add_f32_e32 v100, 1.0, v76
	v_add_f32_e32 v81, 1.0, v81
	v_add_f32_e32 v101, 1.0, v77
	v_rcp_f32_e32 v74, v78
	v_rcp_f32_e32 v76, v98
	v_rcp_f32_e32 v78, v79
	v_rcp_f32_e32 v80, v75
	v_rcp_f32_e32 v75, v99
	v_rcp_f32_e32 v77, v100
	v_rcp_f32_e32 v79, v81
	v_rcp_f32_e32 v81, v101
	s_and_b64 vcc, exec, s[2:3]
	s_waitcnt vmcnt(2)
	v_lshlrev_b32_e32 v99, 16, v87
	v_lshlrev_b32_e32 v98, 16, v86
	v_and_b32_e32 v101, 0xffff0000, v87
	v_and_b32_e32 v100, 0xffff0000, v86
	s_waitcnt vmcnt(1)
	v_mov_b32_e32 v86, v90
	v_mov_b32_e32 v87, v92
	v_mov_b32_e32 v92, v91
	v_lshlrev_b32_e32 v103, 16, v89
	v_lshlrev_b32_e32 v102, 16, v88
	v_and_b32_e32 v105, 0xffff0000, v89
	v_and_b32_e32 v104, 0xffff0000, v88
	s_waitcnt vmcnt(0)
	v_mov_b32_e32 v88, v94
	v_mov_b32_e32 v89, v96
	v_mov_b32_e32 v96, v95
	v_pk_fma_f32 v[86:87], v[74:75], v[98:99], v[86:87]
	v_pk_fma_f32 v[90:91], v[78:79], v[100:101], v[92:93]
	v_pk_fma_f32 v[88:89], v[76:77], v[102:103], v[88:89]
	v_pk_fma_f32 v[92:93], v[80:81], v[104:105], v[96:97]
	v_mov_b32_e32 v78, v86
	v_mov_b32_e32 v79, v90
	v_mov_b32_e32 v80, v87
	v_mov_b32_e32 v81, v91
	v_mov_b32_e32 v74, v88
	v_mov_b32_e32 v75, v92
	v_mov_b32_e32 v76, v89
	v_mov_b32_e32 v77, v93
	v_mov_b32_e32 v94, 0
	global_store_dwordx4 v[84:85], v[78:81], off nt
	global_store_dwordx4 v[84:85], v[74:77], off offset:16 nt
	s_cbranch_vccnz .LBB0_1001
	v_pk_mul_f32 v[90:91], v[90:91], v[90:91]
	v_pk_mul_f32 v[80:81], v[64:65], v[80:81]
	v_pk_fma_f32 v[86:87], v[86:87], v[86:87], v[90:91]
	v_pk_mul_f32 v[90:91], v[92:93], v[92:93]
	v_add_f32_e32 v86, v86, v87
	v_pk_fma_f32 v[88:89], v[88:89], v[88:89], v[90:91]
	v_pk_mul_f32 v[78:79], v[62:63], v[78:79]
	v_add_f32_e32 v86, v88, v86
	v_add_f32_e32 v94, v89, v86
	v_pk_mul_f32 v[86:87], v[60:61], v[76:77]
	v_pk_mul_f32 v[76:77], v[58:59], v[74:75]
	v_cvt_pk_bf16_f32 v74, v78, v79
	v_cvt_pk_bf16_f32 v75, v80, v81
	v_cvt_pk_bf16_f32 v76, v76, v77
	v_cvt_pk_bf16_f32 v77, v86, v87
	v_lshl_add_u64 v[78:79], v[82:83], 1, s[30:31]
	global_store_dwordx4 v[78:79], v[74:77], off
.LBB0_1001:
	v_or_b32_e32 v82, 0x80, v82
	s_nop 0
	v_lshl_add_u64 v[74:75], v[82:83], 1, s[36:37]
	global_load_dwordx4 v[74:77], v[74:75], off
	s_nop 0
	global_load_dwordx4 v[78:81], v[84:85], off offset:512
	global_load_dwordx4 v[86:89], v[84:85], off offset:528
	v_mul_f32_e32 v70, v70, v178
	v_mul_f32_e32 v66, v66, v178
	v_mul_f32_e32 v71, v71, v178
	v_mul_f32_e32 v67, v67, v178
	v_mul_f32_e32 v72, v72, v178
	v_mul_f32_e32 v68, v68, v178
	v_mul_f32_e32 v73, v73, v178
	v_mul_f32_e32 v69, v69, v178
	v_mul_f32_e32 v70, 0xbfb8aa3b, v70
	v_mul_f32_e32 v66, 0xbfb8aa3b, v66
	v_mul_f32_e32 v71, 0xbfb8aa3b, v71
	v_mul_f32_e32 v67, 0xbfb8aa3b, v67
	v_mul_f32_e32 v72, 0xbfb8aa3b, v72
	v_mul_f32_e32 v68, 0xbfb8aa3b, v68
	v_mul_f32_e32 v73, 0xbfb8aa3b, v73
	v_mul_f32_e32 v69, 0xbfb8aa3b, v69
	v_exp_f32_e32 v70, v70
	v_exp_f32_e32 v66, v66
	v_exp_f32_e32 v71, v71
	v_exp_f32_e32 v67, v67
	v_exp_f32_e32 v72, v72
	v_exp_f32_e32 v68, v68
	v_exp_f32_e32 v73, v73
	v_exp_f32_e32 v69, v69
	v_add_f32_e32 v70, 1.0, v70
	v_add_f32_e32 v90, 1.0, v66
	v_add_f32_e32 v71, 1.0, v71
	v_add_f32_e32 v91, 1.0, v67
	v_add_f32_e32 v72, 1.0, v72
	v_add_f32_e32 v92, 1.0, v68
	v_add_f32_e32 v73, 1.0, v73
	v_add_f32_e32 v93, 1.0, v69
	v_rcp_f32_e32 v66, v70
	v_rcp_f32_e32 v68, v90
	v_rcp_f32_e32 v67, v71
	v_rcp_f32_e32 v69, v91
	v_rcp_f32_e32 v72, v72
	v_rcp_f32_e32 v90, v92
	v_rcp_f32_e32 v73, v73
	v_rcp_f32_e32 v91, v93
	s_and_b64 vcc, exec, s[2:3]
	s_waitcnt vmcnt(2)
	v_lshlrev_b32_e32 v70, 16, v74
	v_and_b32_e32 v71, 0xffff0000, v74
	v_lshlrev_b32_e32 v92, 16, v76
	v_and_b32_e32 v93, 0xffff0000, v76
	v_lshlrev_b32_e32 v74, 16, v75
	v_and_b32_e32 v75, 0xffff0000, v75
	v_lshlrev_b32_e32 v76, 16, v77
	v_and_b32_e32 v77, 0xffff0000, v77
	s_waitcnt vmcnt(1)
	v_pk_fma_f32 v[70:71], v[66:67], v[70:71], v[78:79]
	s_waitcnt vmcnt(0)
	v_pk_fma_f32 v[66:67], v[68:69], v[92:93], v[86:87]
	v_pk_fma_f32 v[72:73], v[72:73], v[74:75], v[80:81]
	v_pk_fma_f32 v[68:69], v[90:91], v[76:77], v[88:89]
	global_store_dwordx4 v[84:85], v[70:73], off offset:512 nt
	global_store_dwordx4 v[84:85], v[66:69], off offset:528 nt
	s_cbranch_vccnz .LBB0_1005
	v_pk_mul_f32 v[74:75], v[56:57], v[72:73]
	v_pk_mul_f32 v[76:77], v[54:55], v[70:71]
	v_pk_mul_f32 v[70:71], v[70:71], v[70:71]
	v_pk_mul_f32 v[72:73], v[72:73], v[72:73]
	v_pk_mul_f32 v[80:81], v[66:67], v[66:67]
	v_add_f32_e32 v72, v72, v73
	v_add_f32_e32 v70, v70, v71
	v_pk_mul_f32 v[78:79], v[68:69], v[68:69]
	v_add_f32_e32 v70, v70, v72
	v_add_f32_e32 v71, v80, v81
	v_add_f32_e32 v70, v71, v70
	v_add_f32_e32 v71, v78, v79
	v_add_f32_e32 v70, v71, v70
	v_and_b32_e32 v71, 64, v207
	v_add_f32_e32 v78, v94, v70
	v_xor_b32_e32 v70, 16, v207
	v_add_u32_e32 v79, 64, v71
	v_cmp_lt_i32_e32 vcc, v70, v79
	v_pk_mul_f32 v[72:73], v[52:53], v[68:69]
	v_cvt_pk_bf16_f32 v68, v76, v77
	v_cndmask_b32_e32 v70, v207, v70, vcc
	v_lshlrev_b32_e32 v70, 2, v70
	ds_bpermute_b32 v80, v70, v78
	v_pk_mul_f32 v[70:71], v[50:51], v[66:67]
	v_xor_b32_e32 v67, 32, v207
	v_cmp_lt_i32_e32 vcc, v67, v79
	v_cvt_pk_bf16_f32 v69, v74, v75
	s_waitcnt lgkmcnt(0)
	v_add_f32_e32 v66, v78, v80
	v_cndmask_b32_e32 v67, v207, v67, vcc
	v_lshlrev_b32_e32 v67, 2, v67
	ds_bpermute_b32 v67, v67, v66
	v_cvt_pk_bf16_f32 v70, v70, v71
	v_cvt_pk_bf16_f32 v71, v72, v73
	v_lshl_add_u64 v[72:73], v[82:83], 1, s[30:31]
	global_store_dwordx4 v[72:73], v[68:71], off
	s_and_saveexec_b64 s[48:49], s[38:39]
	s_cbranch_execz .LBB0_1004
	s_add_u32 s76, s28, s46
	s_addc_u32 s77, s29, s47
	v_lshl_add_u64 v[68:69], v[172:173], 2, s[76:77]
	s_waitcnt lgkmcnt(0)
	v_add_f32_e32 v66, v66, v67
	global_store_dword v[68:69], v66, off offset:512

.LBB0_1005:
	s_mov_b64 s[48:49], 0x24000
	s_waitcnt lgkmcnt(0)
	v_lshl_add_u64 v[66:67], v[176:177], 0, s[48:49]
	v_lshl_add_u64 v[68:69], v[66:67], 1, s[36:37]
	global_load_dwordx4 v[70:73], v[68:69], off
	v_lshl_add_u64 v[68:69], v[66:67], 2, s[16:17]
	global_load_dwordx4 v[74:77], v[68:69], off
	global_load_dwordx4 v[78:81], v[68:69], off offset:16
	v_mul_f32_e32 v46, v46, v179
	v_mul_f32_e32 v42, v42, v179
	v_mul_f32_e32 v47, v47, v179
	v_mul_f32_e32 v43, v43, v179
	v_mul_f32_e32 v48, v48, v179
	v_mul_f32_e32 v44, v44, v179
	v_mul_f32_e32 v49, v49, v179
	v_mul_f32_e32 v45, v45, v179
	v_mul_f32_e32 v46, 0xbfb8aa3b, v46
	v_mul_f32_e32 v42, 0xbfb8aa3b, v42
	v_mul_f32_e32 v47, 0xbfb8aa3b, v47
	v_mul_f32_e32 v43, 0xbfb8aa3b, v43
	v_mul_f32_e32 v48, 0xbfb8aa3b, v48
	v_mul_f32_e32 v44, 0xbfb8aa3b, v44
	v_mul_f32_e32 v49, 0xbfb8aa3b, v49
	v_mul_f32_e32 v45, 0xbfb8aa3b, v45
	v_exp_f32_e32 v46, v46
	v_exp_f32_e32 v42, v42
	v_exp_f32_e32 v47, v47
	v_exp_f32_e32 v43, v43
	v_exp_f32_e32 v48, v48
	v_exp_f32_e32 v44, v44
	v_exp_f32_e32 v49, v49
	v_exp_f32_e32 v45, v45
	v_add_f32_e32 v46, 1.0, v46
	v_add_f32_e32 v82, 1.0, v42
	v_add_f32_e32 v47, 1.0, v47
	v_add_f32_e32 v43, 1.0, v43
	v_add_f32_e32 v83, 1.0, v48
	v_add_f32_e32 v84, 1.0, v44
	v_add_f32_e32 v49, 1.0, v49
	v_add_f32_e32 v85, 1.0, v45
	v_rcp_f32_e32 v42, v46
	v_rcp_f32_e32 v44, v82
	v_rcp_f32_e32 v46, v47
	v_rcp_f32_e32 v48, v43
	v_rcp_f32_e32 v43, v83
	v_rcp_f32_e32 v45, v84
	v_rcp_f32_e32 v47, v49
	v_rcp_f32_e32 v49, v85
	s_and_b64 vcc, exec, s[2:3]
	s_waitcnt vmcnt(2)
	v_lshlrev_b32_e32 v83, 16, v71
	v_lshlrev_b32_e32 v82, 16, v70
	v_and_b32_e32 v85, 0xffff0000, v71
	v_and_b32_e32 v84, 0xffff0000, v70
	s_waitcnt vmcnt(1)
	v_mov_b32_e32 v70, v74
	v_mov_b32_e32 v71, v76
	v_mov_b32_e32 v76, v75
	v_lshlrev_b32_e32 v87, 16, v73
	v_lshlrev_b32_e32 v86, 16, v72
	v_and_b32_e32 v89, 0xffff0000, v73
	v_and_b32_e32 v88, 0xffff0000, v72
	s_waitcnt vmcnt(0)
	v_mov_b32_e32 v72, v78
	v_mov_b32_e32 v73, v80
	v_mov_b32_e32 v80, v79
	v_pk_fma_f32 v[70:71], v[42:43], v[82:83], v[70:71]
	v_pk_fma_f32 v[74:75], v[46:47], v[84:85], v[76:77]
	v_pk_fma_f32 v[72:73], v[44:45], v[86:87], v[72:73]
	v_pk_fma_f32 v[76:77], v[48:49], v[88:89], v[80:81]
	v_mov_b32_e32 v46, v70
	v_mov_b32_e32 v47, v74
	v_mov_b32_e32 v48, v71
	v_mov_b32_e32 v49, v75
	v_mov_b32_e32 v42, v72
	v_mov_b32_e32 v43, v76
	v_mov_b32_e32 v44, v73
	v_mov_b32_e32 v45, v77
	v_mov_b32_e32 v78, 0
	global_store_dwordx4 v[68:69], v[46:49], off nt
	global_store_dwordx4 v[68:69], v[42:45], off offset:16 nt
	s_cbranch_vccnz .LBB0_1007
	v_pk_mul_f32 v[74:75], v[74:75], v[74:75]
	v_pk_mul_f32 v[48:49], v[64:65], v[48:49]
	v_pk_fma_f32 v[70:71], v[70:71], v[70:71], v[74:75]
	v_pk_mul_f32 v[74:75], v[76:77], v[76:77]
	v_add_f32_e32 v70, v70, v71
	v_pk_fma_f32 v[72:73], v[72:73], v[72:73], v[74:75]
	v_pk_mul_f32 v[46:47], v[62:63], v[46:47]
	v_add_f32_e32 v70, v72, v70
	v_add_f32_e32 v78, v73, v70
	v_pk_mul_f32 v[70:71], v[60:61], v[44:45]
	v_pk_mul_f32 v[44:45], v[58:59], v[42:43]
	v_cvt_pk_bf16_f32 v42, v46, v47
	v_cvt_pk_bf16_f32 v43, v48, v49
	v_cvt_pk_bf16_f32 v44, v44, v45
	v_cvt_pk_bf16_f32 v45, v70, v71
	v_lshl_add_u64 v[46:47], v[66:67], 1, s[30:31]
	global_store_dwordx4 v[46:47], v[42:45], off
.LBB0_1007:
	v_or_b32_e32 v66, 0x80, v66
	s_nop 0
	v_lshl_add_u64 v[42:43], v[66:67], 1, s[36:37]
	global_load_dwordx4 v[42:45], v[42:43], off
	s_nop 0
	global_load_dwordx4 v[46:49], v[68:69], off offset:512
	global_load_dwordx4 v[70:73], v[68:69], off offset:528
	v_mul_f32_e32 v38, v38, v179
	v_mul_f32_e32 v34, v34, v179
	v_mul_f32_e32 v39, v39, v179
	v_mul_f32_e32 v35, v35, v179
	v_mul_f32_e32 v40, v40, v179
	v_mul_f32_e32 v36, v36, v179
	v_mul_f32_e32 v41, v41, v179
	v_mul_f32_e32 v37, v37, v179
	v_mul_f32_e32 v38, 0xbfb8aa3b, v38
	v_mul_f32_e32 v34, 0xbfb8aa3b, v34
	v_mul_f32_e32 v39, 0xbfb8aa3b, v39
	v_mul_f32_e32 v35, 0xbfb8aa3b, v35
	v_mul_f32_e32 v40, 0xbfb8aa3b, v40
	v_mul_f32_e32 v36, 0xbfb8aa3b, v36
	v_mul_f32_e32 v41, 0xbfb8aa3b, v41
	v_mul_f32_e32 v37, 0xbfb8aa3b, v37
	v_exp_f32_e32 v38, v38
	v_exp_f32_e32 v34, v34
	v_exp_f32_e32 v39, v39
	v_exp_f32_e32 v35, v35
	v_exp_f32_e32 v40, v40
	v_exp_f32_e32 v36, v36
	v_exp_f32_e32 v41, v41
	v_exp_f32_e32 v37, v37
	v_add_f32_e32 v38, 1.0, v38
	v_add_f32_e32 v74, 1.0, v34
	v_add_f32_e32 v39, 1.0, v39
	v_add_f32_e32 v75, 1.0, v35
	v_add_f32_e32 v40, 1.0, v40
	v_add_f32_e32 v76, 1.0, v36
	v_add_f32_e32 v41, 1.0, v41
	v_add_f32_e32 v77, 1.0, v37
	v_rcp_f32_e32 v34, v38
	v_rcp_f32_e32 v36, v74
	v_rcp_f32_e32 v35, v39
	v_rcp_f32_e32 v37, v75
	v_rcp_f32_e32 v40, v40
	v_rcp_f32_e32 v74, v76
	v_rcp_f32_e32 v41, v41
	v_rcp_f32_e32 v75, v77
	s_and_b64 vcc, exec, s[2:3]
	s_waitcnt vmcnt(2)
	v_lshlrev_b32_e32 v38, 16, v42
	v_and_b32_e32 v39, 0xffff0000, v42
	v_lshlrev_b32_e32 v76, 16, v44
	v_and_b32_e32 v77, 0xffff0000, v44
	v_lshlrev_b32_e32 v42, 16, v43
	v_and_b32_e32 v43, 0xffff0000, v43
	v_lshlrev_b32_e32 v44, 16, v45
	v_and_b32_e32 v45, 0xffff0000, v45
	s_waitcnt vmcnt(1)
	v_pk_fma_f32 v[38:39], v[34:35], v[38:39], v[46:47]
	s_waitcnt vmcnt(0)
	v_pk_fma_f32 v[34:35], v[36:37], v[76:77], v[70:71]
	v_pk_fma_f32 v[40:41], v[40:41], v[42:43], v[48:49]
	v_pk_fma_f32 v[36:37], v[74:75], v[44:45], v[72:73]
	global_store_dwordx4 v[68:69], v[38:41], off offset:512 nt
	global_store_dwordx4 v[68:69], v[34:37], off offset:528 nt
	s_cbranch_vccnz .LBB0_1011
	v_pk_mul_f32 v[42:43], v[56:57], v[40:41]
	v_pk_mul_f32 v[44:45], v[54:55], v[38:39]
	v_pk_mul_f32 v[38:39], v[38:39], v[38:39]
	v_pk_mul_f32 v[40:41], v[40:41], v[40:41]
	v_pk_mul_f32 v[48:49], v[34:35], v[34:35]
	v_add_f32_e32 v40, v40, v41
	v_add_f32_e32 v38, v38, v39
	v_pk_mul_f32 v[46:47], v[36:37], v[36:37]
	v_add_f32_e32 v38, v38, v40
	v_add_f32_e32 v39, v48, v49
	v_add_f32_e32 v38, v39, v38
	v_add_f32_e32 v39, v46, v47
	v_add_f32_e32 v38, v39, v38
	v_and_b32_e32 v39, 64, v207
	v_add_f32_e32 v46, v78, v38
	v_xor_b32_e32 v38, 16, v207
	v_add_u32_e32 v47, 64, v39
	v_cmp_lt_i32_e32 vcc, v38, v47
	v_pk_mul_f32 v[40:41], v[52:53], v[36:37]
	v_cvt_pk_bf16_f32 v36, v44, v45
	v_cndmask_b32_e32 v38, v207, v38, vcc
	v_lshlrev_b32_e32 v38, 2, v38
	ds_bpermute_b32 v48, v38, v46
	v_pk_mul_f32 v[38:39], v[50:51], v[34:35]
	v_xor_b32_e32 v35, 32, v207
	v_cmp_lt_i32_e32 vcc, v35, v47
	v_cvt_pk_bf16_f32 v37, v42, v43
	s_waitcnt lgkmcnt(0)
	v_add_f32_e32 v34, v46, v48
	v_cndmask_b32_e32 v35, v207, v35, vcc
	v_lshlrev_b32_e32 v35, 2, v35
	ds_bpermute_b32 v35, v35, v34
	v_cvt_pk_bf16_f32 v38, v38, v39
	v_cvt_pk_bf16_f32 v39, v40, v41
	v_lshl_add_u64 v[40:41], v[66:67], 1, s[30:31]
	global_store_dwordx4 v[40:41], v[36:39], off
	s_and_saveexec_b64 s[48:49], s[38:39]
	s_cbranch_execz .LBB0_1010
	s_add_u32 s76, s28, s46
	s_addc_u32 s77, s29, s47
	v_lshl_add_u64 v[36:37], v[172:173], 2, s[76:77]
	s_waitcnt lgkmcnt(0)
	v_add_f32_e32 v34, v34, v35
	global_store_dword v[36:37], v34, off offset:576

.LBB0_1011:
	s_mov_b64 s[48:49], 0x28000
	s_waitcnt lgkmcnt(0)
	v_lshl_add_u64 v[34:35], v[176:177], 0, s[48:49]
	v_lshl_add_u64 v[36:37], v[34:35], 1, s[36:37]
	global_load_dwordx4 v[38:41], v[36:37], off
	v_lshl_add_u64 v[36:37], v[34:35], 2, s[16:17]
	global_load_dwordx4 v[42:45], v[36:37], off
	global_load_dwordx4 v[46:49], v[36:37], off offset:16
	v_mul_f32_e32 v30, v30, v174
	v_mul_f32_e32 v26, v26, v174
	v_mul_f32_e32 v31, v31, v174
	v_mul_f32_e32 v27, v27, v174
	v_mul_f32_e32 v32, v32, v174
	v_mul_f32_e32 v28, v28, v174
	v_mul_f32_e32 v33, v33, v174
	v_mul_f32_e32 v29, v29, v174
	v_mul_f32_e32 v30, 0xbfb8aa3b, v30
	v_mul_f32_e32 v26, 0xbfb8aa3b, v26
	v_mul_f32_e32 v31, 0xbfb8aa3b, v31
	v_mul_f32_e32 v27, 0xbfb8aa3b, v27
	v_mul_f32_e32 v32, 0xbfb8aa3b, v32
	v_mul_f32_e32 v28, 0xbfb8aa3b, v28
	v_mul_f32_e32 v33, 0xbfb8aa3b, v33
	v_mul_f32_e32 v29, 0xbfb8aa3b, v29
	v_exp_f32_e32 v30, v30
	v_exp_f32_e32 v26, v26
	v_exp_f32_e32 v31, v31
	v_exp_f32_e32 v27, v27
	v_exp_f32_e32 v32, v32
	v_exp_f32_e32 v28, v28
	v_exp_f32_e32 v33, v33
	v_exp_f32_e32 v29, v29
	v_add_f32_e32 v30, 1.0, v30
	v_add_f32_e32 v66, 1.0, v26
	v_add_f32_e32 v31, 1.0, v31
	v_add_f32_e32 v27, 1.0, v27
	v_add_f32_e32 v67, 1.0, v32
	v_add_f32_e32 v68, 1.0, v28
	v_add_f32_e32 v33, 1.0, v33
	v_add_f32_e32 v69, 1.0, v29
	v_rcp_f32_e32 v26, v30
	v_rcp_f32_e32 v28, v66
	v_rcp_f32_e32 v30, v31
	v_rcp_f32_e32 v32, v27
	v_rcp_f32_e32 v27, v67
	v_rcp_f32_e32 v29, v68
	v_rcp_f32_e32 v31, v33
	v_rcp_f32_e32 v33, v69
	s_and_b64 vcc, exec, s[2:3]
	s_waitcnt vmcnt(2)
	v_lshlrev_b32_e32 v67, 16, v39
	v_lshlrev_b32_e32 v66, 16, v38
	v_and_b32_e32 v69, 0xffff0000, v39
	v_and_b32_e32 v68, 0xffff0000, v38
	s_waitcnt vmcnt(1)
	v_mov_b32_e32 v38, v42
	v_mov_b32_e32 v39, v44
	v_mov_b32_e32 v44, v43
	v_lshlrev_b32_e32 v71, 16, v41
	v_lshlrev_b32_e32 v70, 16, v40
	v_and_b32_e32 v73, 0xffff0000, v41
	v_and_b32_e32 v72, 0xffff0000, v40
	s_waitcnt vmcnt(0)
	v_mov_b32_e32 v40, v46
	v_mov_b32_e32 v41, v48
	v_mov_b32_e32 v48, v47
	v_pk_fma_f32 v[38:39], v[26:27], v[66:67], v[38:39]
	v_pk_fma_f32 v[42:43], v[30:31], v[68:69], v[44:45]
	v_pk_fma_f32 v[40:41], v[28:29], v[70:71], v[40:41]
	v_pk_fma_f32 v[44:45], v[32:33], v[72:73], v[48:49]
	v_mov_b32_e32 v30, v38
	v_mov_b32_e32 v31, v42
	v_mov_b32_e32 v32, v39
	v_mov_b32_e32 v33, v43
	v_mov_b32_e32 v26, v40
	v_mov_b32_e32 v27, v44
	v_mov_b32_e32 v28, v41
	v_mov_b32_e32 v29, v45
	v_mov_b32_e32 v46, 0
	global_store_dwordx4 v[36:37], v[30:33], off nt
	global_store_dwordx4 v[36:37], v[26:29], off offset:16 nt
	s_cbranch_vccnz .LBB0_1013
	v_pk_mul_f32 v[42:43], v[42:43], v[42:43]
	v_pk_mul_f32 v[32:33], v[64:65], v[32:33]
	v_pk_fma_f32 v[38:39], v[38:39], v[38:39], v[42:43]
	v_pk_mul_f32 v[42:43], v[44:45], v[44:45]
	v_add_f32_e32 v38, v38, v39
	v_pk_fma_f32 v[40:41], v[40:41], v[40:41], v[42:43]
	v_pk_mul_f32 v[30:31], v[62:63], v[30:31]
	v_add_f32_e32 v38, v40, v38
	v_add_f32_e32 v46, v41, v38
	v_pk_mul_f32 v[38:39], v[60:61], v[28:29]
	v_pk_mul_f32 v[28:29], v[58:59], v[26:27]
	v_cvt_pk_bf16_f32 v26, v30, v31
	v_cvt_pk_bf16_f32 v27, v32, v33
	v_cvt_pk_bf16_f32 v28, v28, v29
	v_cvt_pk_bf16_f32 v29, v38, v39
	v_lshl_add_u64 v[30:31], v[34:35], 1, s[30:31]
	global_store_dwordx4 v[30:31], v[26:29], off
.LBB0_1013:
	v_or_b32_e32 v34, 0x80, v34
	s_nop 0
	v_lshl_add_u64 v[26:27], v[34:35], 1, s[36:37]
	global_load_dwordx4 v[26:29], v[26:27], off
	s_nop 0
	global_load_dwordx4 v[30:33], v[36:37], off offset:512
	global_load_dwordx4 v[38:41], v[36:37], off offset:528
	v_mul_f32_e32 v22, v22, v174
	v_mul_f32_e32 v18, v18, v174
	v_mul_f32_e32 v23, v23, v174
	v_mul_f32_e32 v19, v19, v174
	v_mul_f32_e32 v24, v24, v174
	v_mul_f32_e32 v20, v20, v174
	v_mul_f32_e32 v25, v25, v174
	v_mul_f32_e32 v21, v21, v174
	v_mul_f32_e32 v22, 0xbfb8aa3b, v22
	v_mul_f32_e32 v18, 0xbfb8aa3b, v18
	v_mul_f32_e32 v23, 0xbfb8aa3b, v23
	v_mul_f32_e32 v19, 0xbfb8aa3b, v19
	v_mul_f32_e32 v24, 0xbfb8aa3b, v24
	v_mul_f32_e32 v20, 0xbfb8aa3b, v20
	v_mul_f32_e32 v25, 0xbfb8aa3b, v25
	v_mul_f32_e32 v21, 0xbfb8aa3b, v21
	v_exp_f32_e32 v22, v22
	v_exp_f32_e32 v18, v18
	v_exp_f32_e32 v23, v23
	v_exp_f32_e32 v19, v19
	v_exp_f32_e32 v24, v24
	v_exp_f32_e32 v20, v20
	v_exp_f32_e32 v25, v25
	v_exp_f32_e32 v21, v21
	v_add_f32_e32 v22, 1.0, v22
	v_add_f32_e32 v42, 1.0, v18
	v_add_f32_e32 v23, 1.0, v23
	v_add_f32_e32 v43, 1.0, v19
	v_add_f32_e32 v24, 1.0, v24
	v_add_f32_e32 v44, 1.0, v20
	v_add_f32_e32 v25, 1.0, v25
	v_add_f32_e32 v45, 1.0, v21
	v_rcp_f32_e32 v18, v22
	v_rcp_f32_e32 v20, v42
	v_rcp_f32_e32 v19, v23
	v_rcp_f32_e32 v21, v43
	v_rcp_f32_e32 v24, v24
	v_rcp_f32_e32 v42, v44
	v_rcp_f32_e32 v25, v25
	v_rcp_f32_e32 v43, v45
	s_and_b64 vcc, exec, s[2:3]
	s_waitcnt vmcnt(2)
	v_lshlrev_b32_e32 v22, 16, v26
	v_and_b32_e32 v23, 0xffff0000, v26
	v_lshlrev_b32_e32 v44, 16, v28
	v_and_b32_e32 v45, 0xffff0000, v28
	v_lshlrev_b32_e32 v26, 16, v27
	v_and_b32_e32 v27, 0xffff0000, v27
	v_lshlrev_b32_e32 v28, 16, v29
	v_and_b32_e32 v29, 0xffff0000, v29
	s_waitcnt vmcnt(1)
	v_pk_fma_f32 v[22:23], v[18:19], v[22:23], v[30:31]
	s_waitcnt vmcnt(0)
	v_pk_fma_f32 v[18:19], v[20:21], v[44:45], v[38:39]
	v_pk_fma_f32 v[24:25], v[24:25], v[26:27], v[32:33]
	v_pk_fma_f32 v[20:21], v[42:43], v[28:29], v[40:41]
	global_store_dwordx4 v[36:37], v[22:25], off offset:512 nt
	global_store_dwordx4 v[36:37], v[18:21], off offset:528 nt
	s_cbranch_vccnz .LBB0_1017
	v_pk_mul_f32 v[26:27], v[56:57], v[24:25]
	v_pk_mul_f32 v[28:29], v[54:55], v[22:23]
	v_pk_mul_f32 v[22:23], v[22:23], v[22:23]
	v_pk_mul_f32 v[24:25], v[24:25], v[24:25]
	v_pk_mul_f32 v[32:33], v[18:19], v[18:19]
	v_add_f32_e32 v24, v24, v25
	v_add_f32_e32 v22, v22, v23
	v_pk_mul_f32 v[30:31], v[20:21], v[20:21]
	v_add_f32_e32 v22, v22, v24
	v_add_f32_e32 v23, v32, v33
	v_add_f32_e32 v22, v23, v22
	v_add_f32_e32 v23, v30, v31
	v_add_f32_e32 v22, v23, v22
	v_and_b32_e32 v23, 64, v207
	v_add_f32_e32 v30, v46, v22
	v_xor_b32_e32 v22, 16, v207
	v_add_u32_e32 v31, 64, v23
	v_cmp_lt_i32_e32 vcc, v22, v31
	v_pk_mul_f32 v[24:25], v[52:53], v[20:21]
	v_cvt_pk_bf16_f32 v20, v28, v29
	v_cndmask_b32_e32 v22, v207, v22, vcc
	v_lshlrev_b32_e32 v22, 2, v22
	ds_bpermute_b32 v32, v22, v30
	v_pk_mul_f32 v[22:23], v[50:51], v[18:19]
	v_xor_b32_e32 v19, 32, v207
	v_cmp_lt_i32_e32 vcc, v19, v31
	v_cvt_pk_bf16_f32 v21, v26, v27
	s_waitcnt lgkmcnt(0)
	v_add_f32_e32 v18, v30, v32
	v_cndmask_b32_e32 v19, v207, v19, vcc
	v_lshlrev_b32_e32 v19, 2, v19
	ds_bpermute_b32 v19, v19, v18
	v_cvt_pk_bf16_f32 v22, v22, v23
	v_cvt_pk_bf16_f32 v23, v24, v25
	v_lshl_add_u64 v[24:25], v[34:35], 1, s[30:31]
	global_store_dwordx4 v[24:25], v[20:23], off
	s_and_saveexec_b64 s[48:49], s[38:39]
	s_cbranch_execz .LBB0_1016
	s_add_u32 s76, s28, s46
	s_addc_u32 s77, s29, s47
	v_lshl_add_u64 v[20:21], v[172:173], 2, s[76:77]
	s_waitcnt lgkmcnt(0)
	v_add_f32_e32 v18, v18, v19
	global_store_dword v[20:21], v18, off offset:640

.LBB0_1017:
	s_mov_b64 s[48:49], 0x2c000
	s_waitcnt lgkmcnt(0)
	v_lshl_add_u64 v[18:19], v[176:177], 0, s[48:49]
	v_lshl_add_u64 v[20:21], v[18:19], 1, s[36:37]
	global_load_dwordx4 v[22:25], v[20:21], off
	v_lshl_add_u64 v[20:21], v[18:19], 2, s[16:17]
	global_load_dwordx4 v[26:29], v[20:21], off
	global_load_dwordx4 v[30:33], v[20:21], off offset:16
	v_mul_f32_e32 v14, v14, v175
	v_mul_f32_e32 v10, v10, v175
	v_mul_f32_e32 v15, v15, v175
	v_mul_f32_e32 v11, v11, v175
	v_mul_f32_e32 v16, v16, v175
	v_mul_f32_e32 v12, v12, v175
	v_mul_f32_e32 v17, v17, v175
	v_mul_f32_e32 v13, v13, v175
	v_mul_f32_e32 v14, 0xbfb8aa3b, v14
	v_mul_f32_e32 v10, 0xbfb8aa3b, v10
	v_mul_f32_e32 v15, 0xbfb8aa3b, v15
	v_mul_f32_e32 v11, 0xbfb8aa3b, v11
	v_mul_f32_e32 v16, 0xbfb8aa3b, v16
	v_mul_f32_e32 v12, 0xbfb8aa3b, v12
	v_mul_f32_e32 v17, 0xbfb8aa3b, v17
	v_mul_f32_e32 v13, 0xbfb8aa3b, v13
	v_exp_f32_e32 v14, v14
	v_exp_f32_e32 v10, v10
	v_exp_f32_e32 v15, v15
	v_exp_f32_e32 v11, v11
	v_exp_f32_e32 v16, v16
	v_exp_f32_e32 v12, v12
	v_exp_f32_e32 v17, v17
	v_exp_f32_e32 v13, v13
	v_add_f32_e32 v14, 1.0, v14
	v_add_f32_e32 v34, 1.0, v10
	v_add_f32_e32 v15, 1.0, v15
	v_add_f32_e32 v11, 1.0, v11
	v_add_f32_e32 v35, 1.0, v16
	v_add_f32_e32 v36, 1.0, v12
	v_add_f32_e32 v17, 1.0, v17
	v_add_f32_e32 v37, 1.0, v13
	v_rcp_f32_e32 v10, v14
	v_rcp_f32_e32 v12, v34
	v_rcp_f32_e32 v14, v15
	v_rcp_f32_e32 v16, v11
	v_rcp_f32_e32 v11, v35
	v_rcp_f32_e32 v13, v36
	v_rcp_f32_e32 v15, v17
	v_rcp_f32_e32 v17, v37
	s_and_b64 vcc, exec, s[2:3]
	s_waitcnt vmcnt(2)
	v_lshlrev_b32_e32 v35, 16, v23
	v_lshlrev_b32_e32 v34, 16, v22
	v_and_b32_e32 v37, 0xffff0000, v23
	v_and_b32_e32 v36, 0xffff0000, v22
	s_waitcnt vmcnt(1)
	v_mov_b32_e32 v22, v26
	v_mov_b32_e32 v23, v28
	v_mov_b32_e32 v28, v27
	v_lshlrev_b32_e32 v39, 16, v25
	v_lshlrev_b32_e32 v38, 16, v24
	v_and_b32_e32 v41, 0xffff0000, v25
	v_and_b32_e32 v40, 0xffff0000, v24
	s_waitcnt vmcnt(0)
	v_mov_b32_e32 v24, v30
	v_mov_b32_e32 v25, v32
	v_mov_b32_e32 v32, v31
	v_pk_fma_f32 v[22:23], v[10:11], v[34:35], v[22:23]
	v_pk_fma_f32 v[26:27], v[14:15], v[36:37], v[28:29]
	v_pk_fma_f32 v[24:25], v[12:13], v[38:39], v[24:25]
	v_pk_fma_f32 v[28:29], v[16:17], v[40:41], v[32:33]
	v_mov_b32_e32 v14, v22
	v_mov_b32_e32 v15, v26
	v_mov_b32_e32 v16, v23
	v_mov_b32_e32 v17, v27
	v_mov_b32_e32 v10, v24
	v_mov_b32_e32 v11, v28
	v_mov_b32_e32 v12, v25
	v_mov_b32_e32 v13, v29
	v_mov_b32_e32 v30, 0
	global_store_dwordx4 v[20:21], v[14:17], off nt
	global_store_dwordx4 v[20:21], v[10:13], off offset:16 nt
	s_cbranch_vccnz .LBB0_1019
	v_pk_mul_f32 v[26:27], v[26:27], v[26:27]
	v_pk_mul_f32 v[16:17], v[64:65], v[16:17]
	v_pk_fma_f32 v[22:23], v[22:23], v[22:23], v[26:27]
	v_pk_mul_f32 v[26:27], v[28:29], v[28:29]
	v_add_f32_e32 v22, v22, v23
	v_pk_fma_f32 v[24:25], v[24:25], v[24:25], v[26:27]
	v_pk_mul_f32 v[14:15], v[62:63], v[14:15]
	v_add_f32_e32 v22, v24, v22
	v_add_f32_e32 v30, v25, v22
	v_pk_mul_f32 v[22:23], v[60:61], v[12:13]
	v_pk_mul_f32 v[12:13], v[58:59], v[10:11]
	v_cvt_pk_bf16_f32 v10, v14, v15
	v_cvt_pk_bf16_f32 v11, v16, v17
	v_cvt_pk_bf16_f32 v12, v12, v13
	v_cvt_pk_bf16_f32 v13, v22, v23
	v_lshl_add_u64 v[14:15], v[18:19], 1, s[30:31]
	global_store_dwordx4 v[14:15], v[10:13], off
.LBB0_1019:
	v_or_b32_e32 v18, 0x80, v18
	s_nop 0
	v_lshl_add_u64 v[10:11], v[18:19], 1, s[36:37]
	global_load_dwordx4 v[10:13], v[10:11], off
	s_nop 0
	global_load_dwordx4 v[14:17], v[20:21], off offset:512
	global_load_dwordx4 v[22:25], v[20:21], off offset:528
	v_mul_f32_e32 v6, v6, v175
	v_mul_f32_e32 v2, v2, v175
	v_mul_f32_e32 v7, v7, v175
	v_mul_f32_e32 v3, v3, v175
	v_mul_f32_e32 v8, v8, v175
	v_mul_f32_e32 v4, v4, v175
	v_mul_f32_e32 v9, v9, v175
	v_mul_f32_e32 v5, v5, v175
	v_mul_f32_e32 v6, 0xbfb8aa3b, v6
	v_mul_f32_e32 v2, 0xbfb8aa3b, v2
	v_mul_f32_e32 v7, 0xbfb8aa3b, v7
	v_mul_f32_e32 v3, 0xbfb8aa3b, v3
	v_mul_f32_e32 v8, 0xbfb8aa3b, v8
	v_mul_f32_e32 v4, 0xbfb8aa3b, v4
	v_mul_f32_e32 v9, 0xbfb8aa3b, v9
	v_mul_f32_e32 v5, 0xbfb8aa3b, v5
	v_exp_f32_e32 v6, v6
	v_exp_f32_e32 v2, v2
	v_exp_f32_e32 v7, v7
	v_exp_f32_e32 v3, v3
	v_exp_f32_e32 v8, v8
	v_exp_f32_e32 v4, v4
	v_exp_f32_e32 v9, v9
	v_exp_f32_e32 v5, v5
	v_add_f32_e32 v6, 1.0, v6
	v_add_f32_e32 v26, 1.0, v2
	v_add_f32_e32 v7, 1.0, v7
	v_add_f32_e32 v27, 1.0, v3
	v_add_f32_e32 v8, 1.0, v8
	v_add_f32_e32 v28, 1.0, v4
	v_add_f32_e32 v9, 1.0, v9
	v_add_f32_e32 v29, 1.0, v5
	v_rcp_f32_e32 v2, v6
	v_rcp_f32_e32 v4, v26
	v_rcp_f32_e32 v3, v7
	v_rcp_f32_e32 v5, v27
	v_rcp_f32_e32 v8, v8
	v_rcp_f32_e32 v26, v28
	v_rcp_f32_e32 v9, v9
	v_rcp_f32_e32 v27, v29
	s_and_b64 vcc, exec, s[2:3]
	s_waitcnt vmcnt(2)
	v_lshlrev_b32_e32 v6, 16, v10
	v_and_b32_e32 v7, 0xffff0000, v10
	v_lshlrev_b32_e32 v28, 16, v12
	v_and_b32_e32 v29, 0xffff0000, v12
	v_lshlrev_b32_e32 v10, 16, v11
	v_and_b32_e32 v11, 0xffff0000, v11
	v_lshlrev_b32_e32 v12, 16, v13
	v_and_b32_e32 v13, 0xffff0000, v13
	s_waitcnt vmcnt(1)
	v_pk_fma_f32 v[6:7], v[2:3], v[6:7], v[14:15]
	s_waitcnt vmcnt(0)
	v_pk_fma_f32 v[2:3], v[4:5], v[28:29], v[22:23]
	v_pk_fma_f32 v[8:9], v[8:9], v[10:11], v[16:17]
	v_pk_fma_f32 v[4:5], v[26:27], v[12:13], v[24:25]
	global_store_dwordx4 v[20:21], v[6:9], off offset:512 nt
	global_store_dwordx4 v[20:21], v[2:5], off offset:528 nt
	s_cbranch_vccnz .LBB0_1023
	v_pk_mul_f32 v[12:13], v[56:57], v[8:9]
	v_pk_mul_f32 v[10:11], v[54:55], v[6:7]
	v_pk_mul_f32 v[6:7], v[6:7], v[6:7]
	v_pk_mul_f32 v[8:9], v[8:9], v[8:9]
	v_pk_mul_f32 v[16:17], v[50:51], v[2:3]
	v_pk_mul_f32 v[2:3], v[2:3], v[2:3]
	v_add_f32_e32 v8, v8, v9
	v_add_f32_e32 v6, v6, v7
	v_pk_mul_f32 v[14:15], v[52:53], v[4:5]
	v_pk_mul_f32 v[4:5], v[4:5], v[4:5]
	v_add_f32_e32 v6, v6, v8
	v_add_f32_e32 v2, v2, v3
	v_add_f32_e32 v2, v2, v6
	v_add_f32_e32 v3, v4, v5
	v_and_b32_e32 v4, 64, v207
	v_add_f32_e32 v2, v3, v2
	v_xor_b32_e32 v3, 16, v207
	v_add_u32_e32 v4, 64, v4
	v_cmp_lt_i32_e32 vcc, v3, v4
	v_add_f32_e32 v2, v30, v2
	v_cvt_pk_bf16_f32 v10, v10, v11
	v_cndmask_b32_e32 v3, v207, v3, vcc
	v_lshlrev_b32_e32 v3, 2, v3
	ds_bpermute_b32 v3, v3, v2
	v_cvt_pk_bf16_f32 v11, v12, v13
	v_cvt_pk_bf16_f32 v12, v16, v17
	v_cvt_pk_bf16_f32 v13, v14, v15
	v_lshl_add_u64 v[14:15], v[18:19], 1, s[30:31]
	s_waitcnt lgkmcnt(0)
	v_add_f32_e32 v2, v2, v3
	v_xor_b32_e32 v3, 32, v207
	v_cmp_lt_i32_e32 vcc, v3, v4
	global_store_dwordx4 v[14:15], v[10:13], off
	s_nop 0
	v_cndmask_b32_e32 v3, v207, v3, vcc
	v_lshlrev_b32_e32 v3, 2, v3
	ds_bpermute_b32 v3, v3, v2
	s_and_saveexec_b64 s[2:3], s[38:39]
	s_cbranch_execz .LBB0_1022
	s_add_u32 s46, s28, s46
	s_addc_u32 s47, s29, s47
	v_lshl_add_u64 v[4:5], v[172:173], 2, s[46:47]
	s_waitcnt lgkmcnt(0)
	v_add_f32_e32 v2, v2, v3
	global_store_dword v[4:5], v2, off offset:704
